# v19 plus nt hint on the read-once loads of the weight-conversion phase (f32 weights, adaLN weights) and on the norm phase's x-row loads
# speedup vs baseline: 1.0133x; 1.0087x over previous
.LBB0_7:
	v_ashrrev_i32_e32 v3, 31, v2
	v_lshlrev_b64 v[10:11], 4, v[2:3]
	v_lshl_add_u64 v[6:7], s[10:11], 0, v[10:11]
	global_load_dwordx4 v[6:9], v[6:7], off nt
	v_add_u32_e32 v2, s17, v2
	v_cmp_lt_i32_e32 vcc, s18, v2
	v_lshl_add_u64 v[10:11], s[12:13], 0, v[10:11]
	s_or_b64 s[14:15], vcc, s[14:15]
	s_waitcnt vmcnt(0)
	global_store_dwordx4 v[10:11], v[6:9], off
	s_andn2_b64 exec, exec, s[14:15]
	s_cbranch_execnz .LBB0_7

.LBB0_11:
	s_cmpk_gt_i32 s14, 0x47f
	s_mov_b64 s[8:9], -1
	s_cbranch_scc0 .LBB0_40
	s_cmpk_gt_u32 s14, 0x467f
	s_cbranch_scc0 .LBB0_26
	s_cmpk_gt_u32 s14, 0x4c7f
	s_cbranch_scc0 .LBB0_23
	s_cmpk_gt_u32 s14, 0x4e7f
	s_cbranch_scc0 .LBB0_20
	s_cmpk_gt_u32 s14, 0x517f
	s_cbranch_scc0 .LBB0_17
	s_load_dwordx2 s[10:11], s[70:71], 0x88
	s_lshl_b32 s6, s14, 1
	s_lshl_b32 s8, s14, 5
	s_add_i32 s6, s6, 0x15d00
	s_and_b32 s8, s8, 0x3e0
	s_and_b32 s6, s6, 0x1ffc0
	s_lshl_b32 s9, s8, 2
	s_waitcnt lgkmcnt(0)
	s_add_u32 s10, s10, s9
	v_or_b32_e32 v4, s6, v45
	s_addc_u32 s11, s11, 0
	v_mov_b32_e32 v57, v43
	v_lshl_add_u64 v[2:3], s[10:11], 0, v[56:57]
	v_lshlrev_b32_e32 v42, 12, v4
	v_lshl_add_u64 v[2:3], v[2:3], 0, v[42:43]
	v_add_co_u32_e32 v4, vcc, s20, v2
	s_lshl_b32 s6, s6, 1
	s_nop 0
	v_addc_co_u32_e32 v5, vcc, 0, v3, vcc
	v_add_co_u32_e32 v6, vcc, s21, v2
	s_nop 1
	v_addc_co_u32_e32 v7, vcc, 0, v3, vcc
	v_add_co_u32_e32 v8, vcc, s22, v2
	s_nop 1
	v_addc_co_u32_e32 v9, vcc, 0, v3, vcc
	v_add_co_u32_e32 v10, vcc, s23, v2
	s_nop 1
	v_addc_co_u32_e32 v11, vcc, 0, v3, vcc
	v_add_co_u32_e32 v12, vcc, s24, v2
	s_nop 1
	v_addc_co_u32_e32 v13, vcc, 0, v3, vcc
	v_add_co_u32_e32 v14, vcc, s25, v2
	s_nop 1
	v_addc_co_u32_e32 v15, vcc, 0, v3, vcc
	v_add_co_u32_e32 v16, vcc, s27, v2
	s_nop 1
	v_addc_co_u32_e32 v17, vcc, 0, v3, vcc
	global_load_dword v20, v[2:3], off nt
	global_load_dword v21, v[4:5], off nt
	global_load_dword v22, v[6:7], off nt
	global_load_dword v23, v[8:9], off nt
	global_load_dword v24, v[10:11], off nt
	global_load_dword v25, v[12:13], off nt
	global_load_dword v26, v[14:15], off nt
	global_load_dword v27, v[16:17], off nt
	v_add_co_u32_e32 v4, vcc, s29, v2
	s_nop 1
	v_addc_co_u32_e32 v5, vcc, 0, v3, vcc
	v_add_co_u32_e32 v6, vcc, s30, v2
	s_nop 1
	v_addc_co_u32_e32 v7, vcc, 0, v3, vcc
	v_add_co_u32_e32 v8, vcc, s31, v2
	s_nop 1
	v_addc_co_u32_e32 v9, vcc, 0, v3, vcc
	v_add_co_u32_e32 v10, vcc, s33, v2
	s_nop 1
	v_addc_co_u32_e32 v11, vcc, 0, v3, vcc
	v_add_co_u32_e32 v12, vcc, s34, v2
	s_nop 1
	v_addc_co_u32_e32 v13, vcc, 0, v3, vcc
	v_add_co_u32_e32 v14, vcc, s35, v2
	s_nop 1
	v_addc_co_u32_e32 v15, vcc, 0, v3, vcc
	v_add_co_u32_e32 v16, vcc, s36, v2
	s_nop 1
	v_addc_co_u32_e32 v17, vcc, 0, v3, vcc
	v_add_co_u32_e32 v18, vcc, s37, v2
	s_nop 1
	v_addc_co_u32_e32 v19, vcc, 0, v3, vcc
	global_load_dword v28, v[4:5], off nt
	global_load_dword v29, v[6:7], off nt
	global_load_dword v30, v[8:9], off nt
	global_load_dword v31, v[10:11], off nt
	global_load_dword v32, v[12:13], off nt
	global_load_dword v33, v[14:15], off nt
	global_load_dword v34, v[16:17], off nt
	global_load_dword v35, v[18:19], off nt
	v_add_co_u32_e32 v4, vcc, s38, v2
	s_nop 1
	v_addc_co_u32_e32 v5, vcc, 0, v3, vcc
	v_add_co_u32_e32 v6, vcc, s39, v2
	s_nop 1
	v_addc_co_u32_e32 v7, vcc, 0, v3, vcc
	v_add_co_u32_e32 v8, vcc, s40, v2
	s_nop 1
	v_addc_co_u32_e32 v9, vcc, 0, v3, vcc
	v_add_co_u32_e32 v10, vcc, s41, v2
	s_nop 1
	v_addc_co_u32_e32 v11, vcc, 0, v3, vcc
	v_add_co_u32_e32 v12, vcc, s42, v2
	s_nop 1
	v_addc_co_u32_e32 v13, vcc, 0, v3, vcc
	v_add_co_u32_e32 v14, vcc, s43, v2
	s_nop 1
	v_addc_co_u32_e32 v15, vcc, 0, v3, vcc
	v_add_co_u32_e32 v16, vcc, s44, v2
	s_nop 1
	v_addc_co_u32_e32 v17, vcc, 0, v3, vcc
	v_add_co_u32_e32 v18, vcc, s45, v2
	s_nop 1
	v_addc_co_u32_e32 v19, vcc, 0, v3, vcc
	global_load_dword v36, v[4:5], off nt
	global_load_dword v37, v[6:7], off nt
	global_load_dword v38, v[8:9], off nt
	global_load_dword v39, v[10:11], off nt
	global_load_dword v40, v[12:13], off nt
	global_load_dword v41, v[14:15], off nt
	global_load_dword v42, v[16:17], off nt
	s_nop 0
	global_load_dword v18, v[18:19], off nt
	v_add_co_u32_e32 v4, vcc, s48, v2
	s_nop 1
	v_addc_co_u32_e32 v5, vcc, 0, v3, vcc
	v_add_co_u32_e32 v6, vcc, s49, v2
	s_nop 1
	v_addc_co_u32_e32 v7, vcc, 0, v3, vcc
	v_add_co_u32_e32 v8, vcc, s50, v2
	s_nop 1
	v_addc_co_u32_e32 v9, vcc, 0, v3, vcc
	v_add_co_u32_e32 v10, vcc, s51, v2
	s_nop 1
	v_addc_co_u32_e32 v11, vcc, 0, v3, vcc
	v_add_co_u32_e32 v12, vcc, s52, v2
	s_nop 1
	v_addc_co_u32_e32 v13, vcc, 0, v3, vcc
	v_add_co_u32_e32 v14, vcc, s53, v2
	s_nop 1
	v_addc_co_u32_e32 v15, vcc, 0, v3, vcc
	v_add_co_u32_e32 v16, vcc, s54, v2
	s_nop 1
	v_addc_co_u32_e32 v17, vcc, 0, v3, vcc
	v_add_co_u32_e32 v2, vcc, s55, v2
	s_nop 1
	v_addc_co_u32_e32 v3, vcc, 0, v3, vcc
	global_load_dword v4, v[4:5], off nt
	s_nop 0
	global_load_dword v5, v[6:7], off nt
	s_nop 0
	global_load_dword v6, v[8:9], off nt
	global_load_dword v7, v[10:11], off nt
	s_nop 0
	global_load_dword v8, v[12:13], off nt
	global_load_dword v9, v[14:15], off nt
	global_load_dword v10, v[16:17], off nt
	s_nop 0
	global_load_dword v2, v[2:3], off nt
	s_waitcnt vmcnt(30)
	ds_write2_b32 v55, v20, v21 offset1:66
	s_waitcnt vmcnt(28)
	ds_write2_b32 v55, v22, v23 offset0:132 offset1:198
	s_waitcnt vmcnt(26)
	ds_write2_b32 v92, v24, v25 offset0:8 offset1:74
	s_waitcnt vmcnt(24)
	ds_write2_b32 v92, v26, v27 offset0:140 offset1:206
	s_waitcnt vmcnt(22)
	ds_write2_b32 v93, v28, v29 offset0:16 offset1:82
	s_waitcnt vmcnt(20)
	ds_write2_b32 v93, v30, v31 offset0:148 offset1:214
	s_waitcnt vmcnt(18)
	ds_write2_b32 v94, v32, v33 offset0:24 offset1:90
	s_waitcnt vmcnt(16)
	ds_write2_b32 v94, v34, v35 offset0:156 offset1:222
	s_waitcnt vmcnt(14)
	ds_write2_b32 v95, v36, v37 offset0:32 offset1:98
	s_waitcnt vmcnt(12)
	ds_write2_b32 v95, v38, v39 offset0:164 offset1:230
	s_waitcnt vmcnt(10)
	ds_write2_b32 v96, v40, v41 offset0:40 offset1:106
	s_waitcnt vmcnt(8)
	ds_write2_b32 v96, v42, v18 offset0:172 offset1:238
	s_waitcnt vmcnt(6)
	ds_write2_b32 v97, v4, v5 offset0:48 offset1:114
	s_waitcnt vmcnt(4)
	ds_write2_b32 v97, v6, v7 offset0:180 offset1:246
	s_waitcnt vmcnt(2)
	ds_write2_b32 v98, v8, v9 offset0:56 offset1:122
	s_waitcnt vmcnt(0)
	ds_write2_b32 v98, v10, v2 offset0:188 offset1:254
	s_waitcnt lgkmcnt(0)
	ds_read2_b32 v[6:7], v85 offset0:33 offset1:41
	ds_read2_b32 v[8:9], v85 offset1:8
	ds_read2_b32 v[10:11], v85 offset0:66 offset1:74
	ds_read2_b32 v[12:13], v85 offset0:99 offset1:107
	ds_read2_b32 v[14:15], v85 offset0:132 offset1:140
	ds_read2_b32 v[16:17], v85 offset0:165 offset1:173
	ds_read2_b32 v[18:19], v85 offset0:198 offset1:206
	ds_read2_b32 v[20:21], v85 offset0:231 offset1:239
	s_waitcnt lgkmcnt(6)
	v_cvt_pk_bf16_f32 v2, v8, v6
	v_or_b32_e32 v6, s8, v81
	v_lshl_add_u64 v[22:23], v[46:47], 0, s[6:7]
	v_lshlrev_b32_e32 v42, 11, v6
	s_waitcnt lgkmcnt(4)
	v_cvt_pk_bf16_f32 v3, v10, v12
	s_waitcnt lgkmcnt(2)
	v_cvt_pk_bf16_f32 v4, v14, v16
	s_waitcnt lgkmcnt(0)
	v_cvt_pk_bf16_f32 v5, v18, v20
	v_lshl_add_u64 v[24:25], v[22:23], 0, v[42:43]
	global_store_dwordx4 v[24:25], v[2:5], off
	v_or_b32_e32 v6, s8, v88
	v_lshlrev_b32_e32 v42, 11, v6
	v_cvt_pk_bf16_f32 v2, v9, v7
	v_cvt_pk_bf16_f32 v3, v11, v13
	v_cvt_pk_bf16_f32 v4, v15, v17
	v_cvt_pk_bf16_f32 v5, v19, v21
	ds_read2_b32 v[8:9], v85 offset0:49 offset1:57
	ds_read2_b32 v[10:11], v85 offset0:16 offset1:24
	ds_read2_b32 v[12:13], v85 offset0:82 offset1:90
	ds_read2_b32 v[14:15], v85 offset0:115 offset1:123
	ds_read2_b32 v[16:17], v85 offset0:148 offset1:156
	ds_read2_b32 v[18:19], v85 offset0:181 offset1:189
	ds_read2_b32 v[20:21], v85 offset0:214 offset1:222
	ds_read2_b32 v[24:25], v85 offset0:247 offset1:255
	v_lshl_add_u64 v[6:7], v[22:23], 0, v[42:43]
	global_store_dwordx4 v[6:7], v[2:5], off
	v_or_b32_e32 v6, s8, v89
	v_lshlrev_b32_e32 v42, 11, v6
	s_waitcnt lgkmcnt(6)
	v_cvt_pk_bf16_f32 v2, v10, v8
	s_waitcnt lgkmcnt(4)
	v_cvt_pk_bf16_f32 v3, v12, v14
	s_waitcnt lgkmcnt(2)
	v_cvt_pk_bf16_f32 v4, v16, v18
	s_waitcnt lgkmcnt(0)
	v_cvt_pk_bf16_f32 v5, v20, v24
	v_lshl_add_u64 v[6:7], v[22:23], 0, v[42:43]
	global_store_dwordx4 v[6:7], v[2:5], off
	v_or_b32_e32 v6, s8, v90
	v_lshlrev_b32_e32 v42, 11, v6
	v_cvt_pk_bf16_f32 v2, v11, v9
	v_cvt_pk_bf16_f32 v3, v13, v15
	v_cvt_pk_bf16_f32 v4, v17, v19
	v_cvt_pk_bf16_f32 v5, v21, v25
	v_lshl_add_u64 v[6:7], v[22:23], 0, v[42:43]
	global_store_dwordx4 v[6:7], v[2:5], off
	s_waitcnt lgkmcnt(0)
	s_mov_b64 s[8:9], 0
.LBB0_17:
	s_andn2_b64 vcc, exec, s[8:9]
	s_cbranch_vccnz .LBB0_19
	s_add_i32 s8, s14, 0xb180
	s_and_b32 s6, s8, 0xffff
	s_mul_i32 s6, s6, 0xaaab
	s_lshr_b32 s6, s6, 21
	s_mul_i32 s9, s6, 48
	s_sub_i32 s9, s8, s9
	s_load_dwordx2 s[10:11], s[70:71], 0x80
	s_and_b32 s8, s9, 0xffff
	s_bfe_u32 s12, s9, 0x10002
	s_and_b32 s13, s9, 56
	s_lshl_b32 s9, s9, 1
	s_and_b32 s9, s9, 6
	s_or_b32 s9, s13, s9
	s_or_b32 s9, s9, s12
	s_lshl_b32 s9, s9, 7
	v_lshl_or_b32 v4, s6, 6, v45
	s_waitcnt lgkmcnt(0)
	s_add_u32 s10, s10, s9
	s_addc_u32 s11, s11, 0
	v_mov_b32_e32 v57, v43
	v_mul_u32_u24_e32 v4, 0x600, v4
	v_lshl_add_u64 v[2:3], s[10:11], 0, v[56:57]
	v_lshlrev_b32_e32 v42, 2, v4
	v_lshl_add_u64 v[2:3], v[2:3], 0, v[42:43]
	s_movk_i32 s9, 0x3000
	v_add_co_u32_e32 v4, vcc, s9, v2
	s_mov_b32 s9, 0xf000
	s_nop 0
	v_addc_co_u32_e32 v5, vcc, 0, v3, vcc
	v_add_co_u32_e32 v6, vcc, s22, v2
	s_lshl_b32 s8, s8, 5
	s_nop 0
	v_addc_co_u32_e32 v7, vcc, 0, v3, vcc
	v_add_co_u32_e32 v8, vcc, s56, v2
	s_lshl_b32 s6, s6, 7
	s_nop 0
	v_addc_co_u32_e32 v9, vcc, 0, v3, vcc
	v_add_co_u32_e32 v10, vcc, s25, v2
	s_nop 1
	v_addc_co_u32_e32 v11, vcc, 0, v3, vcc
	v_add_co_u32_e32 v12, vcc, s9, v2
	s_mov_b32 s9, 0x15000
	s_nop 0
	v_addc_co_u32_e32 v13, vcc, 0, v3, vcc
	v_add_co_u32_e32 v14, vcc, s30, v2
	s_nop 1
	v_addc_co_u32_e32 v15, vcc, 0, v3, vcc
	v_add_co_u32_e32 v16, vcc, s9, v2
	s_mov_b32 s9, 0x27000
	s_nop 0
	v_addc_co_u32_e32 v17, vcc, 0, v3, vcc
	global_load_dword v20, v[2:3], off nt
	global_load_dword v21, v[4:5], off nt
	global_load_dword v22, v[6:7], off nt
	global_load_dword v23, v[8:9], off nt
	global_load_dword v24, v[10:11], off nt
	global_load_dword v25, v[12:13], off nt
	global_load_dword v26, v[14:15], off nt
	global_load_dword v27, v[16:17], off nt
	v_add_co_u32_e32 v4, vcc, s34, v2
	s_nop 1
	v_addc_co_u32_e32 v5, vcc, 0, v3, vcc
	v_add_co_u32_e32 v6, vcc, s57, v2
	s_nop 1
	v_addc_co_u32_e32 v7, vcc, 0, v3, vcc
	v_add_co_u32_e32 v8, vcc, s37, v2
	s_nop 1
	v_addc_co_u32_e32 v9, vcc, 0, v3, vcc
	v_add_co_u32_e32 v10, vcc, s58, v2
	s_nop 1
	v_addc_co_u32_e32 v11, vcc, 0, v3, vcc
	v_add_co_u32_e32 v12, vcc, s40, v2
	s_nop 1
	v_addc_co_u32_e32 v13, vcc, 0, v3, vcc
	v_add_co_u32_e32 v14, vcc, s9, v2
	s_mov_b32 s9, 0x33000
	s_nop 0
	v_addc_co_u32_e32 v15, vcc, 0, v3, vcc
	v_add_co_u32_e32 v16, vcc, s43, v2
	s_nop 1
	v_addc_co_u32_e32 v17, vcc, 0, v3, vcc
	v_add_co_u32_e32 v18, vcc, s59, v2
	s_nop 1
	v_addc_co_u32_e32 v19, vcc, 0, v3, vcc
	global_load_dword v28, v[4:5], off nt
	global_load_dword v29, v[6:7], off nt
	global_load_dword v30, v[8:9], off nt
	global_load_dword v31, v[10:11], off nt
	global_load_dword v32, v[12:13], off nt
	global_load_dword v33, v[14:15], off nt
	global_load_dword v34, v[16:17], off nt
	global_load_dword v35, v[18:19], off nt
	v_add_co_u32_e32 v4, vcc, s48, v2
	s_nop 1
	v_addc_co_u32_e32 v5, vcc, 0, v3, vcc
	v_add_co_u32_e32 v6, vcc, s9, v2
	s_mov_b32 s9, 0x39000
	s_nop 0
	v_addc_co_u32_e32 v7, vcc, 0, v3, vcc
	v_add_co_u32_e32 v8, vcc, s51, v2
	s_nop 1
	v_addc_co_u32_e32 v9, vcc, 0, v3, vcc
	v_add_co_u32_e32 v10, vcc, s9, v2
	s_mov_b32 s9, 0x45000
	s_nop 0
	v_addc_co_u32_e32 v11, vcc, 0, v3, vcc
	v_add_co_u32_e32 v12, vcc, s54, v2
	s_nop 1
	v_addc_co_u32_e32 v13, vcc, 0, v3, vcc
	v_add_co_u32_e32 v14, vcc, s60, v2
	s_nop 1
	v_addc_co_u32_e32 v15, vcc, 0, v3, vcc
	v_add_co_u32_e32 v16, vcc, s61, v2
	s_nop 1
	v_addc_co_u32_e32 v17, vcc, 0, v3, vcc
	v_add_co_u32_e32 v18, vcc, s9, v2
	s_mov_b32 s9, 0x4b000
	s_nop 0
	v_addc_co_u32_e32 v19, vcc, 0, v3, vcc
	global_load_dword v36, v[4:5], off nt
	global_load_dword v37, v[6:7], off nt
	global_load_dword v38, v[8:9], off nt
	global_load_dword v39, v[10:11], off nt
	global_load_dword v40, v[12:13], off nt
	global_load_dword v41, v[14:15], off nt
	global_load_dword v42, v[16:17], off nt
	s_nop 0
	global_load_dword v18, v[18:19], off nt
	v_add_co_u32_e32 v4, vcc, s62, v2
	s_nop 1
	v_addc_co_u32_e32 v5, vcc, 0, v3, vcc
	v_add_co_u32_e32 v6, vcc, s9, v2
	s_mov_b32 s9, 0x57000
	s_nop 0
	v_addc_co_u32_e32 v7, vcc, 0, v3, vcc
	v_add_co_u32_e32 v8, vcc, s63, v2
	s_nop 1
	v_addc_co_u32_e32 v9, vcc, 0, v3, vcc
	v_add_co_u32_e32 v10, vcc, s64, v2
	s_nop 1
	v_addc_co_u32_e32 v11, vcc, 0, v3, vcc
	v_add_co_u32_e32 v12, vcc, s65, v2
	s_nop 1
	v_addc_co_u32_e32 v13, vcc, 0, v3, vcc
	v_add_co_u32_e32 v14, vcc, s9, v2
	s_mov_b32 s9, 0x5d000
	s_nop 0
	v_addc_co_u32_e32 v15, vcc, 0, v3, vcc
	v_add_co_u32_e32 v16, vcc, s66, v2
	s_nop 1
	v_addc_co_u32_e32 v17, vcc, 0, v3, vcc
	v_add_co_u32_e32 v2, vcc, s9, v2
	s_nop 1
	v_addc_co_u32_e32 v3, vcc, 0, v3, vcc
	global_load_dword v4, v[4:5], off nt
	s_nop 0
	global_load_dword v5, v[6:7], off nt
	s_nop 0
	global_load_dword v6, v[8:9], off nt
	global_load_dword v7, v[10:11], off nt
	s_nop 0
	global_load_dword v8, v[12:13], off nt
	global_load_dword v9, v[14:15], off nt
	global_load_dword v10, v[16:17], off nt
	s_nop 0
	global_load_dword v2, v[2:3], off nt
	s_waitcnt vmcnt(30)
	ds_write2_b32 v55, v20, v21 offset1:66
	s_waitcnt vmcnt(28)
	ds_write2_b32 v55, v22, v23 offset0:132 offset1:198
	s_waitcnt vmcnt(26)
	ds_write2_b32 v92, v24, v25 offset0:8 offset1:74
	s_waitcnt vmcnt(24)
	ds_write2_b32 v92, v26, v27 offset0:140 offset1:206
	s_waitcnt vmcnt(22)
	ds_write2_b32 v93, v28, v29 offset0:16 offset1:82
	s_waitcnt vmcnt(20)
	ds_write2_b32 v93, v30, v31 offset0:148 offset1:214
	s_waitcnt vmcnt(18)
	ds_write2_b32 v94, v32, v33 offset0:24 offset1:90
	s_waitcnt vmcnt(16)
	ds_write2_b32 v94, v34, v35 offset0:156 offset1:222
	s_waitcnt vmcnt(14)
	ds_write2_b32 v95, v36, v37 offset0:32 offset1:98
	s_waitcnt vmcnt(12)
	ds_write2_b32 v95, v38, v39 offset0:164 offset1:230
	s_waitcnt vmcnt(10)
	ds_write2_b32 v96, v40, v41 offset0:40 offset1:106
	s_waitcnt vmcnt(8)
	ds_write2_b32 v96, v42, v18 offset0:172 offset1:238
	s_waitcnt vmcnt(6)
	ds_write2_b32 v97, v4, v5 offset0:48 offset1:114
	s_waitcnt vmcnt(4)
	ds_write2_b32 v97, v6, v7 offset0:180 offset1:246
	s_waitcnt vmcnt(2)
	ds_write2_b32 v98, v8, v9 offset0:56 offset1:122
	s_waitcnt vmcnt(0)
	ds_write2_b32 v98, v10, v2 offset0:188 offset1:254
	s_waitcnt lgkmcnt(0)
	ds_read2_b32 v[6:7], v85 offset0:33 offset1:41
	ds_read2_b32 v[8:9], v85 offset1:8
	ds_read2_b32 v[10:11], v85 offset0:66 offset1:74
	ds_read2_b32 v[12:13], v85 offset0:99 offset1:107
	ds_read2_b32 v[14:15], v85 offset0:132 offset1:140
	ds_read2_b32 v[16:17], v85 offset0:165 offset1:173
	ds_read2_b32 v[18:19], v85 offset0:198 offset1:206
	ds_read2_b32 v[20:21], v85 offset0:231 offset1:239
	s_waitcnt lgkmcnt(6)
	v_cvt_pk_bf16_f32 v2, v8, v6
	v_or_b32_e32 v6, s8, v81
	v_lshl_add_u64 v[22:23], v[48:49], 0, s[6:7]
	v_lshlrev_b32_e32 v42, 11, v6
	s_waitcnt lgkmcnt(4)
	v_cvt_pk_bf16_f32 v3, v10, v12
	s_waitcnt lgkmcnt(2)
	v_cvt_pk_bf16_f32 v4, v14, v16
	s_waitcnt lgkmcnt(0)
	v_cvt_pk_bf16_f32 v5, v18, v20
	v_lshl_add_u64 v[24:25], v[22:23], 0, v[42:43]
	global_store_dwordx4 v[24:25], v[2:5], off
	v_or_b32_e32 v6, s8, v88
	v_lshlrev_b32_e32 v42, 11, v6
	v_cvt_pk_bf16_f32 v2, v9, v7
	v_cvt_pk_bf16_f32 v3, v11, v13
	v_cvt_pk_bf16_f32 v4, v15, v17
	v_cvt_pk_bf16_f32 v5, v19, v21
	ds_read2_b32 v[8:9], v85 offset0:49 offset1:57
	ds_read2_b32 v[10:11], v85 offset0:16 offset1:24
	ds_read2_b32 v[12:13], v85 offset0:82 offset1:90
	ds_read2_b32 v[14:15], v85 offset0:115 offset1:123
	ds_read2_b32 v[16:17], v85 offset0:148 offset1:156
	ds_read2_b32 v[18:19], v85 offset0:181 offset1:189
	ds_read2_b32 v[20:21], v85 offset0:214 offset1:222
	ds_read2_b32 v[24:25], v85 offset0:247 offset1:255
	v_lshl_add_u64 v[6:7], v[22:23], 0, v[42:43]
	global_store_dwordx4 v[6:7], v[2:5], off
	v_or_b32_e32 v6, s8, v89
	v_lshlrev_b32_e32 v42, 11, v6
	s_waitcnt lgkmcnt(6)
	v_cvt_pk_bf16_f32 v2, v10, v8
	s_waitcnt lgkmcnt(4)
	v_cvt_pk_bf16_f32 v3, v12, v14
	s_waitcnt lgkmcnt(2)
	v_cvt_pk_bf16_f32 v4, v16, v18
	s_waitcnt lgkmcnt(0)
	v_cvt_pk_bf16_f32 v5, v20, v24
	v_lshl_add_u64 v[6:7], v[22:23], 0, v[42:43]
	global_store_dwordx4 v[6:7], v[2:5], off
	v_or_b32_e32 v6, s8, v90
	v_lshlrev_b32_e32 v42, 11, v6
	v_cvt_pk_bf16_f32 v2, v11, v9
	v_cvt_pk_bf16_f32 v3, v13, v15
	v_cvt_pk_bf16_f32 v4, v17, v19
	v_cvt_pk_bf16_f32 v5, v21, v25
	v_lshl_add_u64 v[6:7], v[22:23], 0, v[42:43]
	global_store_dwordx4 v[6:7], v[2:5], off
	s_waitcnt lgkmcnt(0)

.LBB0_20:
	s_andn2_b64 vcc, exec, s[8:9]
	s_cbranch_vccnz .LBB0_22
	s_load_dwordx2 s[10:11], s[70:71], 0x58
	s_lshl_b32 s6, s14, 1
	s_lshl_b32 s8, s14, 5
	s_add_i32 s6, s6, 0x16700
	s_and_b32 s8, s8, 0x3e0
	s_and_b32 s6, s6, 0x1ffc0
	s_lshl_b32 s9, s8, 2
	s_waitcnt lgkmcnt(0)
	s_add_u32 s10, s10, s9
	v_or_b32_e32 v4, s6, v45
	s_addc_u32 s11, s11, 0
	v_mov_b32_e32 v57, v43
	v_lshl_add_u64 v[2:3], s[10:11], 0, v[56:57]
	v_lshlrev_b32_e32 v42, 12, v4
	v_lshl_add_u64 v[2:3], v[2:3], 0, v[42:43]
	v_add_co_u32_e32 v4, vcc, s20, v2
	s_lshl_b32 s6, s6, 1
	s_nop 0
	v_addc_co_u32_e32 v5, vcc, 0, v3, vcc
	v_add_co_u32_e32 v6, vcc, s21, v2
	s_nop 1
	v_addc_co_u32_e32 v7, vcc, 0, v3, vcc
	v_add_co_u32_e32 v8, vcc, s22, v2
	s_nop 1
	v_addc_co_u32_e32 v9, vcc, 0, v3, vcc
	v_add_co_u32_e32 v10, vcc, s23, v2
	s_nop 1
	v_addc_co_u32_e32 v11, vcc, 0, v3, vcc
	v_add_co_u32_e32 v12, vcc, s24, v2
	s_nop 1
	v_addc_co_u32_e32 v13, vcc, 0, v3, vcc
	v_add_co_u32_e32 v14, vcc, s25, v2
	s_nop 1
	v_addc_co_u32_e32 v15, vcc, 0, v3, vcc
	v_add_co_u32_e32 v16, vcc, s27, v2
	s_nop 1
	v_addc_co_u32_e32 v17, vcc, 0, v3, vcc
	global_load_dword v20, v[2:3], off nt
	global_load_dword v21, v[4:5], off nt
	global_load_dword v22, v[6:7], off nt
	global_load_dword v23, v[8:9], off nt
	global_load_dword v24, v[10:11], off nt
	global_load_dword v25, v[12:13], off nt
	global_load_dword v26, v[14:15], off nt
	global_load_dword v27, v[16:17], off nt
	v_add_co_u32_e32 v4, vcc, s29, v2
	s_nop 1
	v_addc_co_u32_e32 v5, vcc, 0, v3, vcc
	v_add_co_u32_e32 v6, vcc, s30, v2
	s_nop 1
	v_addc_co_u32_e32 v7, vcc, 0, v3, vcc
	v_add_co_u32_e32 v8, vcc, s31, v2
	s_nop 1
	v_addc_co_u32_e32 v9, vcc, 0, v3, vcc
	v_add_co_u32_e32 v10, vcc, s33, v2
	s_nop 1
	v_addc_co_u32_e32 v11, vcc, 0, v3, vcc
	v_add_co_u32_e32 v12, vcc, s34, v2
	s_nop 1
	v_addc_co_u32_e32 v13, vcc, 0, v3, vcc
	v_add_co_u32_e32 v14, vcc, s35, v2
	s_nop 1
	v_addc_co_u32_e32 v15, vcc, 0, v3, vcc
	v_add_co_u32_e32 v16, vcc, s36, v2
	s_nop 1
	v_addc_co_u32_e32 v17, vcc, 0, v3, vcc
	v_add_co_u32_e32 v18, vcc, s37, v2
	s_nop 1
	v_addc_co_u32_e32 v19, vcc, 0, v3, vcc
	global_load_dword v28, v[4:5], off nt
	global_load_dword v29, v[6:7], off nt
	global_load_dword v30, v[8:9], off nt
	global_load_dword v31, v[10:11], off nt
	global_load_dword v32, v[12:13], off nt
	global_load_dword v33, v[14:15], off nt
	global_load_dword v34, v[16:17], off nt
	global_load_dword v35, v[18:19], off nt
	v_add_co_u32_e32 v4, vcc, s38, v2
	s_nop 1
	v_addc_co_u32_e32 v5, vcc, 0, v3, vcc
	v_add_co_u32_e32 v6, vcc, s39, v2
	s_nop 1
	v_addc_co_u32_e32 v7, vcc, 0, v3, vcc
	v_add_co_u32_e32 v8, vcc, s40, v2
	s_nop 1
	v_addc_co_u32_e32 v9, vcc, 0, v3, vcc
	v_add_co_u32_e32 v10, vcc, s41, v2
	s_nop 1
	v_addc_co_u32_e32 v11, vcc, 0, v3, vcc
	v_add_co_u32_e32 v12, vcc, s42, v2
	s_nop 1
	v_addc_co_u32_e32 v13, vcc, 0, v3, vcc
	v_add_co_u32_e32 v14, vcc, s43, v2
	s_nop 1
	v_addc_co_u32_e32 v15, vcc, 0, v3, vcc
	v_add_co_u32_e32 v16, vcc, s44, v2
	s_nop 1
	v_addc_co_u32_e32 v17, vcc, 0, v3, vcc
	v_add_co_u32_e32 v18, vcc, s45, v2
	s_nop 1
	v_addc_co_u32_e32 v19, vcc, 0, v3, vcc
	global_load_dword v36, v[4:5], off nt
	global_load_dword v37, v[6:7], off nt
	global_load_dword v38, v[8:9], off nt
	global_load_dword v39, v[10:11], off nt
	global_load_dword v40, v[12:13], off nt
	global_load_dword v41, v[14:15], off nt
	global_load_dword v42, v[16:17], off nt
	s_nop 0
	global_load_dword v18, v[18:19], off nt
	v_add_co_u32_e32 v4, vcc, s48, v2
	s_nop 1
	v_addc_co_u32_e32 v5, vcc, 0, v3, vcc
	v_add_co_u32_e32 v6, vcc, s49, v2
	s_nop 1
	v_addc_co_u32_e32 v7, vcc, 0, v3, vcc
	v_add_co_u32_e32 v8, vcc, s50, v2
	s_nop 1
	v_addc_co_u32_e32 v9, vcc, 0, v3, vcc
	v_add_co_u32_e32 v10, vcc, s51, v2
	s_nop 1
	v_addc_co_u32_e32 v11, vcc, 0, v3, vcc
	v_add_co_u32_e32 v12, vcc, s52, v2
	s_nop 1
	v_addc_co_u32_e32 v13, vcc, 0, v3, vcc
	v_add_co_u32_e32 v14, vcc, s53, v2
	s_nop 1
	v_addc_co_u32_e32 v15, vcc, 0, v3, vcc
	v_add_co_u32_e32 v16, vcc, s54, v2
	s_nop 1
	v_addc_co_u32_e32 v17, vcc, 0, v3, vcc
	v_add_co_u32_e32 v2, vcc, s55, v2
	s_nop 1
	v_addc_co_u32_e32 v3, vcc, 0, v3, vcc
	global_load_dword v4, v[4:5], off nt
	s_nop 0
	global_load_dword v5, v[6:7], off nt
	s_nop 0
	global_load_dword v6, v[8:9], off nt
	global_load_dword v7, v[10:11], off nt
	s_nop 0
	global_load_dword v8, v[12:13], off nt
	global_load_dword v9, v[14:15], off nt
	global_load_dword v10, v[16:17], off nt
	s_nop 0
	global_load_dword v2, v[2:3], off nt
	s_waitcnt vmcnt(30)
	ds_write2_b32 v55, v20, v21 offset1:66
	s_waitcnt vmcnt(28)
	ds_write2_b32 v55, v22, v23 offset0:132 offset1:198
	s_waitcnt vmcnt(26)
	ds_write2_b32 v92, v24, v25 offset0:8 offset1:74
	s_waitcnt vmcnt(24)
	ds_write2_b32 v92, v26, v27 offset0:140 offset1:206
	s_waitcnt vmcnt(22)
	ds_write2_b32 v93, v28, v29 offset0:16 offset1:82
	s_waitcnt vmcnt(20)
	ds_write2_b32 v93, v30, v31 offset0:148 offset1:214
	s_waitcnt vmcnt(18)
	ds_write2_b32 v94, v32, v33 offset0:24 offset1:90
	s_waitcnt vmcnt(16)
	ds_write2_b32 v94, v34, v35 offset0:156 offset1:222
	s_waitcnt vmcnt(14)
	ds_write2_b32 v95, v36, v37 offset0:32 offset1:98
	s_waitcnt vmcnt(12)
	ds_write2_b32 v95, v38, v39 offset0:164 offset1:230
	s_waitcnt vmcnt(10)
	ds_write2_b32 v96, v40, v41 offset0:40 offset1:106
	s_waitcnt vmcnt(8)
	ds_write2_b32 v96, v42, v18 offset0:172 offset1:238
	s_waitcnt vmcnt(6)
	ds_write2_b32 v97, v4, v5 offset0:48 offset1:114
	s_waitcnt vmcnt(4)
	ds_write2_b32 v97, v6, v7 offset0:180 offset1:246
	s_waitcnt vmcnt(2)
	ds_write2_b32 v98, v8, v9 offset0:56 offset1:122
	s_waitcnt vmcnt(0)
	ds_write2_b32 v98, v10, v2 offset0:188 offset1:254
	s_waitcnt lgkmcnt(0)
	ds_read2_b32 v[6:7], v85 offset0:33 offset1:41
	ds_read2_b32 v[8:9], v85 offset1:8
	ds_read2_b32 v[10:11], v85 offset0:66 offset1:74
	ds_read2_b32 v[12:13], v85 offset0:99 offset1:107
	ds_read2_b32 v[14:15], v85 offset0:132 offset1:140
	ds_read2_b32 v[16:17], v85 offset0:165 offset1:173
	ds_read2_b32 v[18:19], v85 offset0:198 offset1:206
	ds_read2_b32 v[20:21], v85 offset0:231 offset1:239
	s_waitcnt lgkmcnt(6)
	v_cvt_pk_bf16_f32 v2, v8, v6
	v_or_b32_e32 v6, s8, v81
	v_lshl_add_u64 v[22:23], v[50:51], 0, s[6:7]
	v_lshlrev_b32_e32 v42, 11, v6
	s_waitcnt lgkmcnt(4)
	v_cvt_pk_bf16_f32 v3, v10, v12
	s_waitcnt lgkmcnt(2)
	v_cvt_pk_bf16_f32 v4, v14, v16
	s_waitcnt lgkmcnt(0)
	v_cvt_pk_bf16_f32 v5, v18, v20
	v_lshl_add_u64 v[24:25], v[22:23], 0, v[42:43]
	global_store_dwordx4 v[24:25], v[2:5], off
	v_or_b32_e32 v6, s8, v88
	v_lshlrev_b32_e32 v42, 11, v6
	v_cvt_pk_bf16_f32 v2, v9, v7
	v_cvt_pk_bf16_f32 v3, v11, v13
	v_cvt_pk_bf16_f32 v4, v15, v17
	v_cvt_pk_bf16_f32 v5, v19, v21
	ds_read2_b32 v[8:9], v85 offset0:49 offset1:57
	ds_read2_b32 v[10:11], v85 offset0:16 offset1:24
	ds_read2_b32 v[12:13], v85 offset0:82 offset1:90
	ds_read2_b32 v[14:15], v85 offset0:115 offset1:123
	ds_read2_b32 v[16:17], v85 offset0:148 offset1:156
	ds_read2_b32 v[18:19], v85 offset0:181 offset1:189
	ds_read2_b32 v[20:21], v85 offset0:214 offset1:222
	ds_read2_b32 v[24:25], v85 offset0:247 offset1:255
	v_lshl_add_u64 v[6:7], v[22:23], 0, v[42:43]
	global_store_dwordx4 v[6:7], v[2:5], off
	v_or_b32_e32 v6, s8, v89
	v_lshlrev_b32_e32 v42, 11, v6
	s_waitcnt lgkmcnt(6)
	v_cvt_pk_bf16_f32 v2, v10, v8
	s_waitcnt lgkmcnt(4)
	v_cvt_pk_bf16_f32 v3, v12, v14
	s_waitcnt lgkmcnt(2)
	v_cvt_pk_bf16_f32 v4, v16, v18
	s_waitcnt lgkmcnt(0)
	v_cvt_pk_bf16_f32 v5, v20, v24
	v_lshl_add_u64 v[6:7], v[22:23], 0, v[42:43]
	global_store_dwordx4 v[6:7], v[2:5], off
	v_or_b32_e32 v6, s8, v90
	v_lshlrev_b32_e32 v42, 11, v6
	v_cvt_pk_bf16_f32 v2, v11, v9
	v_cvt_pk_bf16_f32 v3, v13, v15
	v_cvt_pk_bf16_f32 v4, v17, v19
	v_cvt_pk_bf16_f32 v5, v21, v25
	v_lshl_add_u64 v[6:7], v[22:23], 0, v[42:43]
	global_store_dwordx4 v[6:7], v[2:5], off
	s_waitcnt lgkmcnt(0)

.LBB0_23:
	s_andn2_b64 vcc, exec, s[8:9]
	s_cbranch_vccnz .LBB0_25
	s_add_i32 s6, s14, 0xb980
	s_and_b32 s8, s6, 0xffff
	s_mul_i32 s8, s8, 0xaaab
	s_lshr_b32 s9, s8, 16
	s_lshr_b32 s8, s8, 22
	s_mulk_i32 s8, 0x60
	s_sub_i32 s8, s6, s8
	s_load_dwordx2 s[10:11], s[70:71], 0x50
	s_and_b32 s6, s8, 0xffff
	s_bfe_u32 s12, s8, 0x10002
	s_and_b32 s13, s8, 0x78
	s_lshl_b32 s8, s8, 1
	s_and_b32 s8, s8, 6
	s_or_b32 s8, s13, s8
	s_or_b32 s12, s8, s12
	s_and_b32 s8, s9, 0xffc0
	s_lshl_b32 s9, s12, 7
	v_or_b32_e32 v4, s8, v45
	s_waitcnt lgkmcnt(0)
	s_add_u32 s10, s10, s9
	s_addc_u32 s11, s11, 0
	v_mov_b32_e32 v57, v43
	v_mul_u32_u24_e32 v4, 0xc00, v4
	v_lshl_add_u64 v[2:3], s[10:11], 0, v[56:57]
	v_lshlrev_b32_e32 v42, 2, v4
	v_lshl_add_u64 v[2:3], v[2:3], 0, v[42:43]
	v_add_co_u32_e32 v4, vcc, s22, v2
	s_mov_b32 s9, 0x60000
	s_nop 0
	v_addc_co_u32_e32 v5, vcc, 0, v3, vcc
	v_add_co_u32_e32 v6, vcc, s25, v2
	s_nop 1
	v_addc_co_u32_e32 v7, vcc, 0, v3, vcc
	v_add_co_u32_e32 v8, vcc, s30, v2
	s_nop 1
	v_addc_co_u32_e32 v9, vcc, 0, v3, vcc
	v_add_co_u32_e32 v10, vcc, s34, v2
	s_nop 1
	v_addc_co_u32_e32 v11, vcc, 0, v3, vcc
	v_add_co_u32_e32 v12, vcc, s37, v2
	s_nop 1
	v_addc_co_u32_e32 v13, vcc, 0, v3, vcc
	v_add_co_u32_e32 v14, vcc, s40, v2
	s_nop 1
	v_addc_co_u32_e32 v15, vcc, 0, v3, vcc
	v_add_co_u32_e32 v16, vcc, s43, v2
	s_nop 1
	v_addc_co_u32_e32 v17, vcc, 0, v3, vcc
	global_load_dword v20, v[2:3], off nt
	global_load_dword v21, v[4:5], off nt
	global_load_dword v22, v[6:7], off nt
	global_load_dword v23, v[8:9], off nt
	global_load_dword v24, v[10:11], off nt
	global_load_dword v25, v[12:13], off nt
	global_load_dword v26, v[14:15], off nt
	global_load_dword v27, v[16:17], off nt
	v_add_co_u32_e32 v4, vcc, s48, v2
	s_nop 1
	v_addc_co_u32_e32 v5, vcc, 0, v3, vcc
	v_add_co_u32_e32 v6, vcc, s51, v2
	s_nop 1
	v_addc_co_u32_e32 v7, vcc, 0, v3, vcc
	v_add_co_u32_e32 v8, vcc, s54, v2
	s_nop 1
	v_addc_co_u32_e32 v9, vcc, 0, v3, vcc
	v_add_co_u32_e32 v10, vcc, s61, v2
	s_nop 1
	v_addc_co_u32_e32 v11, vcc, 0, v3, vcc
	v_add_co_u32_e32 v12, vcc, s62, v2
	s_nop 1
	v_addc_co_u32_e32 v13, vcc, 0, v3, vcc
	v_add_co_u32_e32 v14, vcc, s63, v2
	s_nop 1
	v_addc_co_u32_e32 v15, vcc, 0, v3, vcc
	v_add_co_u32_e32 v16, vcc, s65, v2
	s_nop 1
	v_addc_co_u32_e32 v17, vcc, 0, v3, vcc
	v_add_co_u32_e32 v18, vcc, s66, v2
	s_nop 1
	v_addc_co_u32_e32 v19, vcc, 0, v3, vcc
	global_load_dword v28, v[4:5], off nt
	global_load_dword v29, v[6:7], off nt
	global_load_dword v30, v[8:9], off nt
	global_load_dword v31, v[10:11], off nt
	global_load_dword v32, v[12:13], off nt
	global_load_dword v33, v[14:15], off nt
	global_load_dword v34, v[16:17], off nt
	global_load_dword v35, v[18:19], off nt
	v_add_co_u32_e32 v4, vcc, s9, v2
	s_mov_b32 s9, 0x66000
	s_nop 0
	v_addc_co_u32_e32 v5, vcc, 0, v3, vcc
	v_add_co_u32_e32 v6, vcc, s9, v2
	s_mov_b32 s9, 0x72000
	s_nop 0
	v_addc_co_u32_e32 v7, vcc, 0, v3, vcc
	v_add_co_u32_e32 v8, vcc, s67, v2
	s_nop 1
	v_addc_co_u32_e32 v9, vcc, 0, v3, vcc
	v_add_co_u32_e32 v10, vcc, s9, v2
	s_mov_b32 s9, 0x78000
	s_nop 0
	v_addc_co_u32_e32 v11, vcc, 0, v3, vcc
	v_add_co_u32_e32 v12, vcc, s9, v2
	s_mov_b32 s9, 0x8a000
	s_nop 0
	v_addc_co_u32_e32 v13, vcc, 0, v3, vcc
	v_add_co_u32_e32 v14, vcc, s68, v2
	s_nop 1
	v_addc_co_u32_e32 v15, vcc, 0, v3, vcc
	v_add_co_u32_e32 v16, vcc, s69, v2
	s_nop 1
	v_addc_co_u32_e32 v17, vcc, 0, v3, vcc
	v_add_co_u32_e32 v18, vcc, s9, v2
	s_mov_b32 s9, 0x90000
	s_nop 0
	v_addc_co_u32_e32 v19, vcc, 0, v3, vcc
	global_load_dword v36, v[4:5], off nt
	global_load_dword v37, v[6:7], off nt
	global_load_dword v38, v[8:9], off nt
	global_load_dword v39, v[10:11], off nt
	global_load_dword v40, v[12:13], off nt
	global_load_dword v41, v[14:15], off nt
	global_load_dword v42, v[16:17], off nt
	s_nop 0
	global_load_dword v18, v[18:19], off nt
	v_add_co_u32_e32 v4, vcc, s9, v2
	s_mov_b32 s9, 0x96000
	s_nop 0
	v_addc_co_u32_e32 v5, vcc, 0, v3, vcc
	v_add_co_u32_e32 v6, vcc, s9, v2
	s_mov_b32 s9, 0x9c000
	s_nop 0
	v_addc_co_u32_e32 v7, vcc, 0, v3, vcc
	v_add_co_u32_e32 v8, vcc, s9, v2
	s_mov_b32 s9, 0xa2000
	s_nop 0
	v_addc_co_u32_e32 v9, vcc, 0, v3, vcc
	v_add_co_u32_e32 v10, vcc, s9, v2
	s_mov_b32 s9, 0xa8000
	s_nop 0
	v_addc_co_u32_e32 v11, vcc, 0, v3, vcc
	v_add_co_u32_e32 v12, vcc, s9, v2
	s_mov_b32 s9, 0xae000
	s_nop 0
	v_addc_co_u32_e32 v13, vcc, 0, v3, vcc
	v_add_co_u32_e32 v14, vcc, s9, v2
	s_mov_b32 s9, 0xb4000
	s_nop 0
	v_addc_co_u32_e32 v15, vcc, 0, v3, vcc
	v_add_co_u32_e32 v16, vcc, s9, v2
	s_mov_b32 s9, 0xba000
	s_nop 0
	v_addc_co_u32_e32 v17, vcc, 0, v3, vcc
	v_add_co_u32_e32 v2, vcc, s9, v2
	s_lshl_b32 s9, s6, 5
	s_nop 0
	v_addc_co_u32_e32 v3, vcc, 0, v3, vcc
	global_load_dword v4, v[4:5], off nt
	s_nop 0
	global_load_dword v5, v[6:7], off nt
	s_nop 0
	global_load_dword v6, v[8:9], off nt
	global_load_dword v7, v[10:11], off nt
	s_nop 0
	global_load_dword v8, v[12:13], off nt
	global_load_dword v9, v[14:15], off nt
	global_load_dword v10, v[16:17], off nt
	s_nop 0
	global_load_dword v2, v[2:3], off nt
	s_waitcnt vmcnt(30)
	ds_write2_b32 v55, v20, v21 offset1:66
	s_waitcnt vmcnt(28)
	ds_write2_b32 v55, v22, v23 offset0:132 offset1:198
	s_waitcnt vmcnt(26)
	ds_write2_b32 v92, v24, v25 offset0:8 offset1:74
	s_waitcnt vmcnt(24)
	ds_write2_b32 v92, v26, v27 offset0:140 offset1:206
	s_waitcnt vmcnt(22)
	ds_write2_b32 v93, v28, v29 offset0:16 offset1:82
	s_waitcnt vmcnt(20)
	ds_write2_b32 v93, v30, v31 offset0:148 offset1:214
	s_waitcnt vmcnt(18)
	ds_write2_b32 v94, v32, v33 offset0:24 offset1:90
	s_waitcnt vmcnt(16)
	ds_write2_b32 v94, v34, v35 offset0:156 offset1:222
	s_waitcnt vmcnt(14)
	ds_write2_b32 v95, v36, v37 offset0:32 offset1:98
	s_waitcnt vmcnt(12)
	ds_write2_b32 v95, v38, v39 offset0:164 offset1:230
	s_waitcnt vmcnt(10)
	ds_write2_b32 v96, v40, v41 offset0:40 offset1:106
	s_waitcnt vmcnt(8)
	ds_write2_b32 v96, v42, v18 offset0:172 offset1:238
	s_waitcnt vmcnt(6)
	ds_write2_b32 v97, v4, v5 offset0:48 offset1:114
	s_waitcnt vmcnt(4)
	ds_write2_b32 v97, v6, v7 offset0:180 offset1:246
	s_waitcnt vmcnt(2)
	ds_write2_b32 v98, v8, v9 offset0:56 offset1:122
	s_waitcnt vmcnt(0)
	ds_write2_b32 v98, v10, v2 offset0:188 offset1:254
	s_waitcnt lgkmcnt(0)
	ds_read2_b32 v[6:7], v85 offset0:33 offset1:41
	ds_read2_b32 v[8:9], v85 offset1:8
	ds_read2_b32 v[10:11], v85 offset0:66 offset1:74
	ds_read2_b32 v[12:13], v85 offset0:99 offset1:107
	ds_read2_b32 v[14:15], v85 offset0:132 offset1:140
	ds_read2_b32 v[16:17], v85 offset0:165 offset1:173
	ds_read2_b32 v[18:19], v85 offset0:198 offset1:206
	ds_read2_b32 v[20:21], v85 offset0:231 offset1:239
	s_lshl_b32 s6, s8, 1
	s_waitcnt lgkmcnt(6)
	v_cvt_pk_bf16_f32 v2, v8, v6
	v_or_b32_e32 v6, s9, v81
	v_lshl_add_u64 v[22:23], v[52:53], 0, s[6:7]
	v_lshlrev_b32_e32 v42, 11, v6
	s_waitcnt lgkmcnt(4)
	v_cvt_pk_bf16_f32 v3, v10, v12
	s_waitcnt lgkmcnt(2)
	v_cvt_pk_bf16_f32 v4, v14, v16
	s_waitcnt lgkmcnt(0)
	v_cvt_pk_bf16_f32 v5, v18, v20
	v_lshl_add_u64 v[24:25], v[22:23], 0, v[42:43]
	global_store_dwordx4 v[24:25], v[2:5], off
	v_or_b32_e32 v6, s9, v88
	v_lshlrev_b32_e32 v42, 11, v6
	v_cvt_pk_bf16_f32 v2, v9, v7
	v_cvt_pk_bf16_f32 v3, v11, v13
	v_cvt_pk_bf16_f32 v4, v15, v17
	v_cvt_pk_bf16_f32 v5, v19, v21
	ds_read2_b32 v[8:9], v85 offset0:49 offset1:57
	ds_read2_b32 v[10:11], v85 offset0:16 offset1:24
	ds_read2_b32 v[12:13], v85 offset0:82 offset1:90
	ds_read2_b32 v[14:15], v85 offset0:115 offset1:123
	ds_read2_b32 v[16:17], v85 offset0:148 offset1:156
	ds_read2_b32 v[18:19], v85 offset0:181 offset1:189
	ds_read2_b32 v[20:21], v85 offset0:214 offset1:222
	ds_read2_b32 v[24:25], v85 offset0:247 offset1:255
	v_lshl_add_u64 v[6:7], v[22:23], 0, v[42:43]
	global_store_dwordx4 v[6:7], v[2:5], off
	v_or_b32_e32 v6, s9, v89
	v_lshlrev_b32_e32 v42, 11, v6
	s_waitcnt lgkmcnt(6)
	v_cvt_pk_bf16_f32 v2, v10, v8
	s_waitcnt lgkmcnt(4)
	v_cvt_pk_bf16_f32 v3, v12, v14
	s_waitcnt lgkmcnt(2)
	v_cvt_pk_bf16_f32 v4, v16, v18
	s_waitcnt lgkmcnt(0)
	v_cvt_pk_bf16_f32 v5, v20, v24
	v_lshl_add_u64 v[6:7], v[22:23], 0, v[42:43]
	global_store_dwordx4 v[6:7], v[2:5], off
	v_or_b32_e32 v6, s9, v90
	v_lshlrev_b32_e32 v42, 11, v6
	v_cvt_pk_bf16_f32 v2, v11, v9
	v_cvt_pk_bf16_f32 v3, v13, v15
	v_cvt_pk_bf16_f32 v4, v17, v19
	v_cvt_pk_bf16_f32 v5, v21, v25
	v_lshl_add_u64 v[6:7], v[22:23], 0, v[42:43]
	global_store_dwordx4 v[6:7], v[2:5], off
	s_waitcnt lgkmcnt(0)

.LBB0_26:
	s_andn2_b64 vcc, exec, s[8:9]
	s_cbranch_vccnz .LBB0_39
	s_add_i32 s6, s14, 0xfffffb80
	s_cmpk_gt_u32 s6, 0x20ff
	s_cselect_b64 s[8:9], -1, 0
	s_and_b64 s[10:11], s[8:9], exec
	s_cselect_b32 s13, 0xffffdf00, 0
	s_add_i32 s13, s13, s6
	s_and_b64 s[10:11], s[8:9], exec
	s_cselect_b32 s6, 0x2100000, 0
	s_add_u32 s6, s18, s6
	s_addc_u32 s12, s19, 0
	s_cmpk_gt_i32 s13, 0xaff
	s_mov_b64 s[10:11], -1
	s_cbranch_scc0 .LBB0_37
	s_cmpk_gt_u32 s13, 0x107f
	s_cbranch_scc0 .LBB0_34
	s_cmpk_gt_u32 s13, 0x1b7f
	s_cbranch_scc0 .LBB0_31
	s_load_dwordx2 s[10:11], s[70:71], 0x48
	s_and_b64 s[46:47], s[8:9], exec
	s_cselect_b32 s46, 0xb00000, 0
	v_mov_b32_e32 v57, v43
	s_waitcnt lgkmcnt(0)
	s_add_u32 s46, s10, s46
	s_addc_u32 s47, s11, 0
	s_lshl_b32 s10, s13, 1
	s_lshl_b32 s97, s14, 5
	s_add_i32 s10, s10, 0x1c900
	s_and_b32 s11, s10, 0x1ffc0
	s_and_b32 s10, s97, 0x3e0
	s_lshl_b32 s97, s10, 2
	s_add_u32 s46, s46, s97
	v_or_b32_e32 v4, s11, v45
	s_addc_u32 s47, s47, 0
	v_lshl_add_u64 v[2:3], s[46:47], 0, v[56:57]
	v_lshlrev_b32_e32 v42, 12, v4
	v_lshl_add_u64 v[2:3], v[2:3], 0, v[42:43]
	v_add_co_u32_e32 v4, vcc, s20, v2
	s_lshl_b32 s11, s11, 1
	s_nop 0
	v_addc_co_u32_e32 v5, vcc, 0, v3, vcc
	v_add_co_u32_e32 v6, vcc, s21, v2
	s_add_u32 s46, s6, s11
	s_nop 0
	v_addc_co_u32_e32 v7, vcc, 0, v3, vcc
	v_add_co_u32_e32 v8, vcc, s22, v2
	s_addc_u32 s47, s12, 0
	s_nop 0
	v_addc_co_u32_e32 v9, vcc, 0, v3, vcc
	v_add_co_u32_e32 v10, vcc, s23, v2
	s_nop 1
	v_addc_co_u32_e32 v11, vcc, 0, v3, vcc
	v_add_co_u32_e32 v12, vcc, s24, v2
	s_nop 1
	v_addc_co_u32_e32 v13, vcc, 0, v3, vcc
	v_add_co_u32_e32 v14, vcc, s25, v2
	s_nop 1
	v_addc_co_u32_e32 v15, vcc, 0, v3, vcc
	v_add_co_u32_e32 v16, vcc, s27, v2
	s_nop 1
	v_addc_co_u32_e32 v17, vcc, 0, v3, vcc
	global_load_dword v20, v[2:3], off nt
	global_load_dword v21, v[4:5], off nt
	global_load_dword v22, v[6:7], off nt
	global_load_dword v23, v[8:9], off nt
	global_load_dword v24, v[10:11], off nt
	global_load_dword v25, v[12:13], off nt
	global_load_dword v26, v[14:15], off nt
	global_load_dword v27, v[16:17], off nt
	v_add_co_u32_e32 v4, vcc, s29, v2
	s_nop 1
	v_addc_co_u32_e32 v5, vcc, 0, v3, vcc
	v_add_co_u32_e32 v6, vcc, s30, v2
	s_nop 1
	v_addc_co_u32_e32 v7, vcc, 0, v3, vcc
	v_add_co_u32_e32 v8, vcc, s31, v2
	s_nop 1
	v_addc_co_u32_e32 v9, vcc, 0, v3, vcc
	v_add_co_u32_e32 v10, vcc, s33, v2
	s_nop 1
	v_addc_co_u32_e32 v11, vcc, 0, v3, vcc
	v_add_co_u32_e32 v12, vcc, s34, v2
	s_nop 1
	v_addc_co_u32_e32 v13, vcc, 0, v3, vcc
	v_add_co_u32_e32 v14, vcc, s35, v2
	s_nop 1
	v_addc_co_u32_e32 v15, vcc, 0, v3, vcc
	v_add_co_u32_e32 v16, vcc, s36, v2
	s_nop 1
	v_addc_co_u32_e32 v17, vcc, 0, v3, vcc
	v_add_co_u32_e32 v18, vcc, s37, v2
	s_nop 1
	v_addc_co_u32_e32 v19, vcc, 0, v3, vcc
	global_load_dword v28, v[4:5], off nt
	global_load_dword v29, v[6:7], off nt
	global_load_dword v30, v[8:9], off nt
	global_load_dword v31, v[10:11], off nt
	global_load_dword v32, v[12:13], off nt
	global_load_dword v33, v[14:15], off nt
	global_load_dword v34, v[16:17], off nt
	global_load_dword v35, v[18:19], off nt
	v_add_co_u32_e32 v4, vcc, s38, v2
	s_nop 1
	v_addc_co_u32_e32 v5, vcc, 0, v3, vcc
	v_add_co_u32_e32 v6, vcc, s39, v2
	s_nop 1
	v_addc_co_u32_e32 v7, vcc, 0, v3, vcc
	v_add_co_u32_e32 v8, vcc, s40, v2
	s_nop 1
	v_addc_co_u32_e32 v9, vcc, 0, v3, vcc
	v_add_co_u32_e32 v10, vcc, s41, v2
	s_nop 1
	v_addc_co_u32_e32 v11, vcc, 0, v3, vcc
	v_add_co_u32_e32 v12, vcc, s42, v2
	s_nop 1
	v_addc_co_u32_e32 v13, vcc, 0, v3, vcc
	v_add_co_u32_e32 v14, vcc, s43, v2
	s_nop 1
	v_addc_co_u32_e32 v15, vcc, 0, v3, vcc
	v_add_co_u32_e32 v16, vcc, s44, v2
	s_nop 1
	v_addc_co_u32_e32 v17, vcc, 0, v3, vcc
	v_add_co_u32_e32 v18, vcc, s45, v2
	s_nop 1
	v_addc_co_u32_e32 v19, vcc, 0, v3, vcc
	global_load_dword v36, v[4:5], off nt
	global_load_dword v37, v[6:7], off nt
	global_load_dword v38, v[8:9], off nt
	global_load_dword v39, v[10:11], off nt
	global_load_dword v40, v[12:13], off nt
	global_load_dword v41, v[14:15], off nt
	global_load_dword v42, v[16:17], off nt
	s_nop 0
	global_load_dword v18, v[18:19], off nt
	v_add_co_u32_e32 v4, vcc, s48, v2
	s_nop 1
	v_addc_co_u32_e32 v5, vcc, 0, v3, vcc
	v_add_co_u32_e32 v6, vcc, s49, v2
	s_nop 1
	v_addc_co_u32_e32 v7, vcc, 0, v3, vcc
	v_add_co_u32_e32 v8, vcc, s50, v2
	s_nop 1
	v_addc_co_u32_e32 v9, vcc, 0, v3, vcc
	v_add_co_u32_e32 v10, vcc, s51, v2
	s_nop 1
	v_addc_co_u32_e32 v11, vcc, 0, v3, vcc
	v_add_co_u32_e32 v12, vcc, s52, v2
	s_nop 1
	v_addc_co_u32_e32 v13, vcc, 0, v3, vcc
	v_add_co_u32_e32 v14, vcc, s53, v2
	s_nop 1
	v_addc_co_u32_e32 v15, vcc, 0, v3, vcc
	v_add_co_u32_e32 v16, vcc, s54, v2
	s_nop 1
	v_addc_co_u32_e32 v17, vcc, 0, v3, vcc
	v_add_co_u32_e32 v2, vcc, s55, v2
	s_nop 1
	v_addc_co_u32_e32 v3, vcc, 0, v3, vcc
	global_load_dword v4, v[4:5], off nt
	s_nop 0
	global_load_dword v5, v[6:7], off nt
	s_nop 0
	global_load_dword v6, v[8:9], off nt
	global_load_dword v7, v[10:11], off nt
	s_nop 0
	global_load_dword v8, v[12:13], off nt
	global_load_dword v9, v[14:15], off nt
	global_load_dword v10, v[16:17], off nt
	s_nop 0
	global_load_dword v2, v[2:3], off nt
	s_waitcnt vmcnt(30)
	ds_write2_b32 v55, v20, v21 offset1:66
	s_waitcnt vmcnt(28)
	ds_write2_b32 v55, v22, v23 offset0:132 offset1:198
	s_waitcnt vmcnt(26)
	ds_write2_b32 v92, v24, v25 offset0:8 offset1:74
	s_waitcnt vmcnt(24)
	ds_write2_b32 v92, v26, v27 offset0:140 offset1:206
	s_waitcnt vmcnt(22)
	ds_write2_b32 v93, v28, v29 offset0:16 offset1:82
	s_waitcnt vmcnt(20)
	ds_write2_b32 v93, v30, v31 offset0:148 offset1:214
	s_waitcnt vmcnt(18)
	ds_write2_b32 v94, v32, v33 offset0:24 offset1:90
	s_waitcnt vmcnt(16)
	ds_write2_b32 v94, v34, v35 offset0:156 offset1:222
	s_waitcnt vmcnt(14)
	ds_write2_b32 v95, v36, v37 offset0:32 offset1:98
	s_waitcnt vmcnt(12)
	ds_write2_b32 v95, v38, v39 offset0:164 offset1:230
	s_waitcnt vmcnt(10)
	ds_write2_b32 v96, v40, v41 offset0:40 offset1:106
	s_waitcnt vmcnt(8)
	ds_write2_b32 v96, v42, v18 offset0:172 offset1:238
	s_waitcnt vmcnt(6)
	ds_write2_b32 v97, v4, v5 offset0:48 offset1:114
	s_waitcnt vmcnt(4)
	ds_write2_b32 v97, v6, v7 offset0:180 offset1:246
	s_waitcnt vmcnt(2)
	ds_write2_b32 v98, v8, v9 offset0:56 offset1:122
	s_waitcnt vmcnt(0)
	ds_write2_b32 v98, v10, v2 offset0:188 offset1:254
	s_waitcnt lgkmcnt(0)
	v_lshlrev_b32_e32 v42, 1, v44
	ds_read2_b32 v[6:7], v85 offset0:33 offset1:41
	ds_read2_b32 v[8:9], v85 offset1:8
	ds_read2_b32 v[10:11], v85 offset0:66 offset1:74
	ds_read2_b32 v[12:13], v85 offset0:99 offset1:107
	ds_read2_b32 v[14:15], v85 offset0:132 offset1:140
	ds_read2_b32 v[16:17], v85 offset0:165 offset1:173
	ds_read2_b32 v[18:19], v85 offset0:198 offset1:206
	ds_read2_b32 v[20:21], v85 offset0:231 offset1:239
	v_lshl_add_u64 v[2:3], s[46:47], 0, v[42:43]
	s_mov_b64 s[46:47], 0x1b80000
	v_lshl_add_u64 v[22:23], v[2:3], 0, s[46:47]
	s_waitcnt lgkmcnt(6)
	v_cvt_pk_bf16_f32 v2, v8, v6
	v_or_b32_e32 v6, s10, v81
	v_mul_u32_u24_e32 v6, 0xb00, v6
	v_lshlrev_b32_e32 v42, 1, v6
	s_waitcnt lgkmcnt(4)
	v_cvt_pk_bf16_f32 v3, v10, v12
	s_waitcnt lgkmcnt(2)
	v_cvt_pk_bf16_f32 v4, v14, v16
	s_waitcnt lgkmcnt(0)
	v_cvt_pk_bf16_f32 v5, v18, v20
	v_lshl_add_u64 v[24:25], v[22:23], 0, v[42:43]
	v_or_b32_e32 v6, s10, v88
	global_store_dwordx4 v[24:25], v[2:5], off
	v_mul_u32_u24_e32 v6, 0xb00, v6
	v_lshlrev_b32_e32 v42, 1, v6
	v_cvt_pk_bf16_f32 v2, v9, v7
	v_cvt_pk_bf16_f32 v3, v11, v13
	v_cvt_pk_bf16_f32 v4, v15, v17
	v_cvt_pk_bf16_f32 v5, v19, v21
	ds_read2_b32 v[8:9], v85 offset0:16 offset1:24
	ds_read2_b32 v[10:11], v85 offset0:49 offset1:57
	ds_read2_b32 v[12:13], v85 offset0:82 offset1:90
	ds_read2_b32 v[14:15], v85 offset0:115 offset1:123
	ds_read2_b32 v[16:17], v85 offset0:148 offset1:156
	ds_read2_b32 v[18:19], v85 offset0:181 offset1:189
	ds_read2_b32 v[20:21], v85 offset0:214 offset1:222
	ds_read2_b32 v[24:25], v85 offset0:247 offset1:255
	v_lshl_add_u64 v[6:7], v[22:23], 0, v[42:43]
	global_store_dwordx4 v[6:7], v[2:5], off
	v_or_b32_e32 v6, s10, v89
	v_mul_u32_u24_e32 v6, 0xb00, v6
	v_lshlrev_b32_e32 v42, 1, v6
	s_waitcnt lgkmcnt(6)
	v_cvt_pk_bf16_f32 v2, v8, v10
	s_waitcnt lgkmcnt(4)
	v_cvt_pk_bf16_f32 v3, v12, v14
	s_waitcnt lgkmcnt(2)
	v_cvt_pk_bf16_f32 v4, v16, v18
	s_waitcnt lgkmcnt(0)
	v_cvt_pk_bf16_f32 v5, v20, v24
	v_lshl_add_u64 v[6:7], v[22:23], 0, v[42:43]
	global_store_dwordx4 v[6:7], v[2:5], off
	v_or_b32_e32 v6, s10, v90
	v_mul_u32_u24_e32 v6, 0xb00, v6
	v_lshlrev_b32_e32 v42, 1, v6
	v_cvt_pk_bf16_f32 v2, v9, v11
	v_cvt_pk_bf16_f32 v3, v13, v15
	v_cvt_pk_bf16_f32 v4, v17, v19
	v_cvt_pk_bf16_f32 v5, v21, v25
	v_lshl_add_u64 v[6:7], v[22:23], 0, v[42:43]
	global_store_dwordx4 v[6:7], v[2:5], off
	s_waitcnt lgkmcnt(0)
	s_mov_b64 s[10:11], 0
.LBB0_31:
	s_andn2_b64 vcc, exec, s[10:11]
	s_cbranch_vccnz .LBB0_33
	s_load_dwordx2 s[10:11], s[70:71], 0x40
	s_and_b64 s[46:47], s[8:9], exec
	s_cselect_b32 s46, 0x1600000, 0
	v_mov_b32_e32 v57, v43
	s_waitcnt lgkmcnt(0)
	s_add_u32 s46, s10, s46
	s_addc_u32 s47, s11, 0
	s_add_i32 s11, s13, 0xef80
	s_and_b32 s10, s11, 0xffff
	s_mul_i32 s10, s10, 0xba2f
	s_lshr_b32 s10, s10, 23
	s_mul_i32 s97, s10, 0xb0
	s_sub_i32 s97, s11, s97
	s_and_b32 s11, s97, 0xffff
	s_and_b32 s98, s97, 3
	s_bitcmp0_b32 s97, 2
	s_cselect_b32 s99, 0, 0x58
	s_lshr_b32 s97, s97, 1
	s_and_b32 s97, s97, 0x7c
	s_add_i32 s99, s99, s97
	s_or_b32 s97, s99, s98
	s_lshl_b32 s97, s97, 7
	v_lshl_or_b32 v4, s10, 6, v45
	s_add_u32 s46, s46, s97
	s_addc_u32 s47, s47, 0
	v_mul_u32_u24_e32 v4, 0x1600, v4
	v_lshl_add_u64 v[2:3], s[46:47], 0, v[56:57]
	v_lshlrev_b32_e32 v42, 2, v4
	v_lshl_add_u64 v[2:3], v[2:3], 0, v[42:43]
	v_add_co_u32_e32 v4, vcc, s0, v2
	s_lshl_b32 s46, s11, 5
	s_nop 0
	v_addc_co_u32_e32 v5, vcc, 0, v3, vcc
	v_add_co_u32_e32 v6, vcc, s33, v2
	s_lshl_b32 s10, s10, 7
	s_nop 0
	v_addc_co_u32_e32 v7, vcc, 0, v3, vcc
	v_add_co_u32_e32 v8, vcc, s58, v2
	s_add_u32 s10, s6, s10
	s_nop 0
	v_addc_co_u32_e32 v9, vcc, 0, v3, vcc
	v_add_co_u32_e32 v10, vcc, s44, v2
	s_addc_u32 s11, s12, 0
	s_nop 0
	v_addc_co_u32_e32 v11, vcc, 0, v3, vcc
	v_add_co_u32_e32 v12, vcc, s1, v2
	s_nop 1
	v_addc_co_u32_e32 v13, vcc, 0, v3, vcc
	v_add_co_u32_e32 v14, vcc, s61, v2
	s_nop 1
	v_addc_co_u32_e32 v15, vcc, 0, v3, vcc
	v_add_co_u32_e32 v16, vcc, s72, v2
	s_nop 1
	v_addc_co_u32_e32 v17, vcc, 0, v3, vcc
	global_load_dword v20, v[2:3], off nt
	global_load_dword v21, v[4:5], off nt
	global_load_dword v22, v[6:7], off nt
	global_load_dword v23, v[8:9], off nt
	global_load_dword v24, v[10:11], off nt
	global_load_dword v25, v[12:13], off nt
	global_load_dword v26, v[14:15], off nt
	global_load_dword v27, v[16:17], off nt
	v_add_co_u32_e32 v4, vcc, s73, v2
	s_nop 1
	v_addc_co_u32_e32 v5, vcc, 0, v3, vcc
	v_add_co_u32_e32 v6, vcc, s74, v2
	s_nop 1
	v_addc_co_u32_e32 v7, vcc, 0, v3, vcc
	v_add_co_u32_e32 v8, vcc, s75, v2
	s_nop 1
	v_addc_co_u32_e32 v9, vcc, 0, v3, vcc
	v_add_co_u32_e32 v10, vcc, s76, v2
	s_nop 1
	v_addc_co_u32_e32 v11, vcc, 0, v3, vcc
	v_add_co_u32_e32 v12, vcc, s69, v2
	s_nop 1
	v_addc_co_u32_e32 v13, vcc, 0, v3, vcc
	v_add_co_u32_e32 v14, vcc, s77, v2
	s_nop 1
	v_addc_co_u32_e32 v15, vcc, 0, v3, vcc
	v_add_co_u32_e32 v16, vcc, s79, v2
	s_nop 1
	v_addc_co_u32_e32 v17, vcc, 0, v3, vcc
	v_add_co_u32_e32 v18, vcc, s80, v2
	s_nop 1
	v_addc_co_u32_e32 v19, vcc, 0, v3, vcc
	global_load_dword v28, v[4:5], off nt
	global_load_dword v29, v[6:7], off nt
	global_load_dword v30, v[8:9], off nt
	global_load_dword v31, v[10:11], off nt
	global_load_dword v32, v[12:13], off nt
	global_load_dword v33, v[14:15], off nt
	global_load_dword v34, v[16:17], off nt
	global_load_dword v35, v[18:19], off nt
	v_add_co_u32_e32 v4, vcc, s81, v2
	s_nop 1
	v_addc_co_u32_e32 v5, vcc, 0, v3, vcc
	v_add_co_u32_e32 v6, vcc, s82, v2
	s_nop 1
	v_addc_co_u32_e32 v7, vcc, 0, v3, vcc
	v_add_co_u32_e32 v8, vcc, s83, v2
	s_nop 1
	v_addc_co_u32_e32 v9, vcc, 0, v3, vcc
	v_add_co_u32_e32 v10, vcc, s84, v2
	s_nop 1
	v_addc_co_u32_e32 v11, vcc, 0, v3, vcc
	v_add_co_u32_e32 v12, vcc, s85, v2
	s_nop 1
	v_addc_co_u32_e32 v13, vcc, 0, v3, vcc
	v_add_co_u32_e32 v14, vcc, s86, v2
	s_nop 1
	v_addc_co_u32_e32 v15, vcc, 0, v3, vcc
	v_add_co_u32_e32 v16, vcc, s87, v2
	s_nop 1
	v_addc_co_u32_e32 v17, vcc, 0, v3, vcc
	v_add_co_u32_e32 v18, vcc, s88, v2
	s_nop 1
	v_addc_co_u32_e32 v19, vcc, 0, v3, vcc
	global_load_dword v36, v[4:5], off nt
	global_load_dword v37, v[6:7], off nt
	global_load_dword v38, v[8:9], off nt
	global_load_dword v39, v[10:11], off nt
	global_load_dword v40, v[12:13], off nt
	global_load_dword v41, v[14:15], off nt
	global_load_dword v42, v[16:17], off nt
	s_nop 0
	global_load_dword v18, v[18:19], off nt
	v_add_co_u32_e32 v4, vcc, s89, v2
	s_nop 1
	v_addc_co_u32_e32 v5, vcc, 0, v3, vcc
	v_add_co_u32_e32 v6, vcc, s90, v2
	s_nop 1
	v_addc_co_u32_e32 v7, vcc, 0, v3, vcc
	v_add_co_u32_e32 v8, vcc, s91, v2
	s_nop 1
	v_addc_co_u32_e32 v9, vcc, 0, v3, vcc
	v_add_co_u32_e32 v10, vcc, s92, v2
	s_nop 1
	v_addc_co_u32_e32 v11, vcc, 0, v3, vcc
	v_add_co_u32_e32 v12, vcc, s93, v2
	s_nop 1
	v_addc_co_u32_e32 v13, vcc, 0, v3, vcc
	v_add_co_u32_e32 v14, vcc, s94, v2
	s_nop 1
	v_addc_co_u32_e32 v15, vcc, 0, v3, vcc
	v_add_co_u32_e32 v16, vcc, s95, v2
	s_nop 1
	v_addc_co_u32_e32 v17, vcc, 0, v3, vcc
	v_add_co_u32_e32 v2, vcc, s96, v2
	s_nop 1
	v_addc_co_u32_e32 v3, vcc, 0, v3, vcc
	global_load_dword v4, v[4:5], off nt
	s_nop 0
	global_load_dword v5, v[6:7], off nt
	s_nop 0
	global_load_dword v6, v[8:9], off nt
	global_load_dword v7, v[10:11], off nt
	s_nop 0
	global_load_dword v8, v[12:13], off nt
	global_load_dword v9, v[14:15], off nt
	global_load_dword v10, v[16:17], off nt
	s_nop 0
	global_load_dword v2, v[2:3], off nt
	s_waitcnt vmcnt(30)
	ds_write2_b32 v55, v20, v21 offset1:66
	s_waitcnt vmcnt(28)
	ds_write2_b32 v55, v22, v23 offset0:132 offset1:198
	s_waitcnt vmcnt(26)
	ds_write2_b32 v92, v24, v25 offset0:8 offset1:74
	s_waitcnt vmcnt(24)
	ds_write2_b32 v92, v26, v27 offset0:140 offset1:206
	s_waitcnt vmcnt(22)
	ds_write2_b32 v93, v28, v29 offset0:16 offset1:82
	s_waitcnt vmcnt(20)
	ds_write2_b32 v93, v30, v31 offset0:148 offset1:214
	s_waitcnt vmcnt(18)
	ds_write2_b32 v94, v32, v33 offset0:24 offset1:90
	s_waitcnt vmcnt(16)
	ds_write2_b32 v94, v34, v35 offset0:156 offset1:222
	s_waitcnt vmcnt(14)
	ds_write2_b32 v95, v36, v37 offset0:32 offset1:98
	s_waitcnt vmcnt(12)
	ds_write2_b32 v95, v38, v39 offset0:164 offset1:230
	s_waitcnt vmcnt(10)
	ds_write2_b32 v96, v40, v41 offset0:40 offset1:106
	s_waitcnt vmcnt(8)
	ds_write2_b32 v96, v42, v18 offset0:172 offset1:238
	s_waitcnt vmcnt(6)
	ds_write2_b32 v97, v4, v5 offset0:48 offset1:114
	s_waitcnt vmcnt(4)
	ds_write2_b32 v97, v6, v7 offset0:180 offset1:246
	s_waitcnt vmcnt(2)
	ds_write2_b32 v98, v8, v9 offset0:56 offset1:122
	s_waitcnt vmcnt(0)
	ds_write2_b32 v98, v10, v2 offset0:188 offset1:254
	s_waitcnt lgkmcnt(0)
	ds_read2_b32 v[6:7], v85 offset0:33 offset1:41
	ds_read2_b32 v[8:9], v85 offset1:8
	ds_read2_b32 v[10:11], v85 offset0:66 offset1:74
	ds_read2_b32 v[12:13], v85 offset0:99 offset1:107
	ds_read2_b32 v[14:15], v85 offset0:132 offset1:140
	ds_read2_b32 v[16:17], v85 offset0:165 offset1:173
	ds_read2_b32 v[18:19], v85 offset0:198 offset1:206
	ds_read2_b32 v[20:21], v85 offset0:231 offset1:239
	v_lshlrev_b32_e32 v42, 1, v44
	v_lshl_add_u64 v[2:3], s[10:11], 0, v[42:43]
	s_mov_b64 s[10:11], 0x1080000
	v_lshl_add_u64 v[22:23], v[2:3], 0, s[10:11]
	s_waitcnt lgkmcnt(6)
	v_cvt_pk_bf16_f32 v2, v8, v6
	v_or_b32_e32 v6, s46, v81
	v_lshlrev_b32_e32 v42, 11, v6
	s_waitcnt lgkmcnt(4)
	v_cvt_pk_bf16_f32 v3, v10, v12
	s_waitcnt lgkmcnt(2)
	v_cvt_pk_bf16_f32 v4, v14, v16
	s_waitcnt lgkmcnt(0)
	v_cvt_pk_bf16_f32 v5, v18, v20
	v_lshl_add_u64 v[24:25], v[22:23], 0, v[42:43]
	global_store_dwordx4 v[24:25], v[2:5], off
	v_or_b32_e32 v6, s46, v88
	v_lshlrev_b32_e32 v42, 11, v6
	v_cvt_pk_bf16_f32 v2, v9, v7
	v_cvt_pk_bf16_f32 v3, v11, v13
	v_cvt_pk_bf16_f32 v4, v15, v17
	v_cvt_pk_bf16_f32 v5, v19, v21
	ds_read2_b32 v[8:9], v85 offset0:49 offset1:57
	ds_read2_b32 v[10:11], v85 offset0:16 offset1:24
	ds_read2_b32 v[12:13], v85 offset0:82 offset1:90
	ds_read2_b32 v[14:15], v85 offset0:115 offset1:123
	ds_read2_b32 v[16:17], v85 offset0:148 offset1:156
	ds_read2_b32 v[18:19], v85 offset0:181 offset1:189
	ds_read2_b32 v[20:21], v85 offset0:214 offset1:222
	ds_read2_b32 v[24:25], v85 offset0:247 offset1:255
	v_lshl_add_u64 v[6:7], v[22:23], 0, v[42:43]
	global_store_dwordx4 v[6:7], v[2:5], off
	v_or_b32_e32 v6, s46, v89
	v_lshlrev_b32_e32 v42, 11, v6
	s_waitcnt lgkmcnt(6)
	v_cvt_pk_bf16_f32 v2, v10, v8
	s_waitcnt lgkmcnt(4)
	v_cvt_pk_bf16_f32 v3, v12, v14
	s_waitcnt lgkmcnt(2)
	v_cvt_pk_bf16_f32 v4, v16, v18
	s_waitcnt lgkmcnt(0)
	v_cvt_pk_bf16_f32 v5, v20, v24
	v_lshl_add_u64 v[6:7], v[22:23], 0, v[42:43]
	global_store_dwordx4 v[6:7], v[2:5], off
	v_or_b32_e32 v6, s46, v90
	v_lshlrev_b32_e32 v42, 11, v6
	v_cvt_pk_bf16_f32 v2, v11, v9
	v_cvt_pk_bf16_f32 v3, v13, v15
	v_cvt_pk_bf16_f32 v4, v17, v19
	v_cvt_pk_bf16_f32 v5, v21, v25
	v_lshl_add_u64 v[6:7], v[22:23], 0, v[42:43]
	global_store_dwordx4 v[6:7], v[2:5], off
	s_waitcnt lgkmcnt(0)

.LBB0_34:
	s_andn2_b64 vcc, exec, s[10:11]
	s_cbranch_vccnz .LBB0_36
	s_load_dwordx2 s[10:11], s[70:71], 0x38
	s_and_b64 s[46:47], s[8:9], exec
	s_cselect_b32 s46, 0xb00000, 0
	v_mov_b32_e32 v57, v43
	s_waitcnt lgkmcnt(0)
	s_add_u32 s46, s10, s46
	s_addc_u32 s47, s11, 0
	s_lshl_b32 s10, s13, 1
	s_lshl_b32 s97, s14, 5
	s_add_i32 s10, s10, 0x1ea00
	s_and_b32 s11, s10, 0x1ffc0
	s_and_b32 s10, s97, 0x3e0
	s_lshl_b32 s97, s10, 2
	s_add_u32 s46, s46, s97
	v_or_b32_e32 v4, s11, v45
	s_addc_u32 s47, s47, 0
	v_lshl_add_u64 v[2:3], s[46:47], 0, v[56:57]
	v_lshlrev_b32_e32 v42, 12, v4
	v_lshl_add_u64 v[2:3], v[2:3], 0, v[42:43]
	v_add_co_u32_e32 v4, vcc, s20, v2
	s_lshl_b32 s11, s11, 1
	s_nop 0
	v_addc_co_u32_e32 v5, vcc, 0, v3, vcc
	v_add_co_u32_e32 v6, vcc, s21, v2
	s_add_u32 s46, s6, s11
	s_nop 0
	v_addc_co_u32_e32 v7, vcc, 0, v3, vcc
	v_add_co_u32_e32 v8, vcc, s22, v2
	s_addc_u32 s47, s12, 0
	s_nop 0
	v_addc_co_u32_e32 v9, vcc, 0, v3, vcc
	v_add_co_u32_e32 v10, vcc, s23, v2
	s_nop 1
	v_addc_co_u32_e32 v11, vcc, 0, v3, vcc
	v_add_co_u32_e32 v12, vcc, s24, v2
	s_nop 1
	v_addc_co_u32_e32 v13, vcc, 0, v3, vcc
	v_add_co_u32_e32 v14, vcc, s25, v2
	s_nop 1
	v_addc_co_u32_e32 v15, vcc, 0, v3, vcc
	v_add_co_u32_e32 v16, vcc, s27, v2
	s_nop 1
	v_addc_co_u32_e32 v17, vcc, 0, v3, vcc
	global_load_dword v20, v[2:3], off nt
	global_load_dword v21, v[4:5], off nt
	global_load_dword v22, v[6:7], off nt
	global_load_dword v23, v[8:9], off nt
	global_load_dword v24, v[10:11], off nt
	global_load_dword v25, v[12:13], off nt
	global_load_dword v26, v[14:15], off nt
	global_load_dword v27, v[16:17], off nt
	v_add_co_u32_e32 v4, vcc, s29, v2
	s_nop 1
	v_addc_co_u32_e32 v5, vcc, 0, v3, vcc
	v_add_co_u32_e32 v6, vcc, s30, v2
	s_nop 1
	v_addc_co_u32_e32 v7, vcc, 0, v3, vcc
	v_add_co_u32_e32 v8, vcc, s31, v2
	s_nop 1
	v_addc_co_u32_e32 v9, vcc, 0, v3, vcc
	v_add_co_u32_e32 v10, vcc, s33, v2
	s_nop 1
	v_addc_co_u32_e32 v11, vcc, 0, v3, vcc
	v_add_co_u32_e32 v12, vcc, s34, v2
	s_nop 1
	v_addc_co_u32_e32 v13, vcc, 0, v3, vcc
	v_add_co_u32_e32 v14, vcc, s35, v2
	s_nop 1
	v_addc_co_u32_e32 v15, vcc, 0, v3, vcc
	v_add_co_u32_e32 v16, vcc, s36, v2
	s_nop 1
	v_addc_co_u32_e32 v17, vcc, 0, v3, vcc
	v_add_co_u32_e32 v18, vcc, s37, v2
	s_nop 1
	v_addc_co_u32_e32 v19, vcc, 0, v3, vcc
	global_load_dword v28, v[4:5], off nt
	global_load_dword v29, v[6:7], off nt
	global_load_dword v30, v[8:9], off nt
	global_load_dword v31, v[10:11], off nt
	global_load_dword v32, v[12:13], off nt
	global_load_dword v33, v[14:15], off nt
	global_load_dword v34, v[16:17], off nt
	global_load_dword v35, v[18:19], off nt
	v_add_co_u32_e32 v4, vcc, s38, v2
	s_nop 1
	v_addc_co_u32_e32 v5, vcc, 0, v3, vcc
	v_add_co_u32_e32 v6, vcc, s39, v2
	s_nop 1
	v_addc_co_u32_e32 v7, vcc, 0, v3, vcc
	v_add_co_u32_e32 v8, vcc, s40, v2
	s_nop 1
	v_addc_co_u32_e32 v9, vcc, 0, v3, vcc
	v_add_co_u32_e32 v10, vcc, s41, v2
	s_nop 1
	v_addc_co_u32_e32 v11, vcc, 0, v3, vcc
	v_add_co_u32_e32 v12, vcc, s42, v2
	s_nop 1
	v_addc_co_u32_e32 v13, vcc, 0, v3, vcc
	v_add_co_u32_e32 v14, vcc, s43, v2
	s_nop 1
	v_addc_co_u32_e32 v15, vcc, 0, v3, vcc
	v_add_co_u32_e32 v16, vcc, s44, v2
	s_nop 1
	v_addc_co_u32_e32 v17, vcc, 0, v3, vcc
	v_add_co_u32_e32 v18, vcc, s45, v2
	s_nop 1
	v_addc_co_u32_e32 v19, vcc, 0, v3, vcc
	global_load_dword v36, v[4:5], off nt
	global_load_dword v37, v[6:7], off nt
	global_load_dword v38, v[8:9], off nt
	global_load_dword v39, v[10:11], off nt
	global_load_dword v40, v[12:13], off nt
	global_load_dword v41, v[14:15], off nt
	global_load_dword v42, v[16:17], off nt
	s_nop 0
	global_load_dword v18, v[18:19], off nt
	v_add_co_u32_e32 v4, vcc, s48, v2
	s_nop 1
	v_addc_co_u32_e32 v5, vcc, 0, v3, vcc
	v_add_co_u32_e32 v6, vcc, s49, v2
	s_nop 1
	v_addc_co_u32_e32 v7, vcc, 0, v3, vcc
	v_add_co_u32_e32 v8, vcc, s50, v2
	s_nop 1
	v_addc_co_u32_e32 v9, vcc, 0, v3, vcc
	v_add_co_u32_e32 v10, vcc, s51, v2
	s_nop 1
	v_addc_co_u32_e32 v11, vcc, 0, v3, vcc
	v_add_co_u32_e32 v12, vcc, s52, v2
	s_nop 1
	v_addc_co_u32_e32 v13, vcc, 0, v3, vcc
	v_add_co_u32_e32 v14, vcc, s53, v2
	s_nop 1
	v_addc_co_u32_e32 v15, vcc, 0, v3, vcc
	v_add_co_u32_e32 v16, vcc, s54, v2
	s_nop 1
	v_addc_co_u32_e32 v17, vcc, 0, v3, vcc
	v_add_co_u32_e32 v2, vcc, s55, v2
	s_nop 1
	v_addc_co_u32_e32 v3, vcc, 0, v3, vcc
	global_load_dword v4, v[4:5], off nt
	s_nop 0
	global_load_dword v5, v[6:7], off nt
	s_nop 0
	global_load_dword v6, v[8:9], off nt
	global_load_dword v7, v[10:11], off nt
	s_nop 0
	global_load_dword v8, v[12:13], off nt
	global_load_dword v9, v[14:15], off nt
	global_load_dword v10, v[16:17], off nt
	s_nop 0
	global_load_dword v2, v[2:3], off nt
	s_waitcnt vmcnt(30)
	ds_write2_b32 v55, v20, v21 offset1:66
	s_waitcnt vmcnt(28)
	ds_write2_b32 v55, v22, v23 offset0:132 offset1:198
	s_waitcnt vmcnt(26)
	ds_write2_b32 v92, v24, v25 offset0:8 offset1:74
	s_waitcnt vmcnt(24)
	ds_write2_b32 v92, v26, v27 offset0:140 offset1:206
	s_waitcnt vmcnt(22)
	ds_write2_b32 v93, v28, v29 offset0:16 offset1:82
	s_waitcnt vmcnt(20)
	ds_write2_b32 v93, v30, v31 offset0:148 offset1:214
	s_waitcnt vmcnt(18)
	ds_write2_b32 v94, v32, v33 offset0:24 offset1:90
	s_waitcnt vmcnt(16)
	ds_write2_b32 v94, v34, v35 offset0:156 offset1:222
	s_waitcnt vmcnt(14)
	ds_write2_b32 v95, v36, v37 offset0:32 offset1:98
	s_waitcnt vmcnt(12)
	ds_write2_b32 v95, v38, v39 offset0:164 offset1:230
	s_waitcnt vmcnt(10)
	ds_write2_b32 v96, v40, v41 offset0:40 offset1:106
	s_waitcnt vmcnt(8)
	ds_write2_b32 v96, v42, v18 offset0:172 offset1:238
	s_waitcnt vmcnt(6)
	ds_write2_b32 v97, v4, v5 offset0:48 offset1:114
	s_waitcnt vmcnt(4)
	ds_write2_b32 v97, v6, v7 offset0:180 offset1:246
	s_waitcnt vmcnt(2)
	ds_write2_b32 v98, v8, v9 offset0:56 offset1:122
	s_waitcnt vmcnt(0)
	ds_write2_b32 v98, v10, v2 offset0:188 offset1:254
	s_waitcnt lgkmcnt(0)
	v_lshlrev_b32_e32 v42, 1, v44
	ds_read2_b32 v[6:7], v85 offset0:33 offset1:41
	ds_read2_b32 v[8:9], v85 offset1:8
	ds_read2_b32 v[10:11], v85 offset0:66 offset1:74
	ds_read2_b32 v[12:13], v85 offset0:99 offset1:107
	ds_read2_b32 v[14:15], v85 offset0:132 offset1:140
	ds_read2_b32 v[16:17], v85 offset0:165 offset1:173
	ds_read2_b32 v[18:19], v85 offset0:198 offset1:206
	ds_read2_b32 v[20:21], v85 offset0:231 offset1:239
	v_lshl_add_u64 v[2:3], s[46:47], 0, v[42:43]
	s_mov_b64 s[46:47], 0xb00000
	v_lshl_add_u64 v[22:23], v[2:3], 0, s[46:47]
	s_waitcnt lgkmcnt(6)
	v_cvt_pk_bf16_f32 v2, v8, v6
	v_or_b32_e32 v6, s10, v81
	v_mul_u32_u24_e32 v6, 0xb00, v6
	v_lshlrev_b32_e32 v42, 1, v6
	s_waitcnt lgkmcnt(4)
	v_cvt_pk_bf16_f32 v3, v10, v12
	s_waitcnt lgkmcnt(2)
	v_cvt_pk_bf16_f32 v4, v14, v16
	s_waitcnt lgkmcnt(0)
	v_cvt_pk_bf16_f32 v5, v18, v20
	v_lshl_add_u64 v[24:25], v[22:23], 0, v[42:43]
	v_or_b32_e32 v6, s10, v88
	global_store_dwordx4 v[24:25], v[2:5], off
	v_mul_u32_u24_e32 v6, 0xb00, v6
	v_lshlrev_b32_e32 v42, 1, v6
	v_cvt_pk_bf16_f32 v2, v9, v7
	v_cvt_pk_bf16_f32 v3, v11, v13
	v_cvt_pk_bf16_f32 v4, v15, v17
	v_cvt_pk_bf16_f32 v5, v19, v21
	ds_read2_b32 v[8:9], v85 offset0:16 offset1:24
	ds_read2_b32 v[10:11], v85 offset0:49 offset1:57
	ds_read2_b32 v[12:13], v85 offset0:82 offset1:90
	ds_read2_b32 v[14:15], v85 offset0:115 offset1:123
	ds_read2_b32 v[16:17], v85 offset0:148 offset1:156
	ds_read2_b32 v[18:19], v85 offset0:181 offset1:189
	ds_read2_b32 v[20:21], v85 offset0:214 offset1:222
	ds_read2_b32 v[24:25], v85 offset0:247 offset1:255
	v_lshl_add_u64 v[6:7], v[22:23], 0, v[42:43]
	global_store_dwordx4 v[6:7], v[2:5], off
	v_or_b32_e32 v6, s10, v89
	v_mul_u32_u24_e32 v6, 0xb00, v6
	v_lshlrev_b32_e32 v42, 1, v6
	s_waitcnt lgkmcnt(6)
	v_cvt_pk_bf16_f32 v2, v8, v10
	s_waitcnt lgkmcnt(4)
	v_cvt_pk_bf16_f32 v3, v12, v14
	s_waitcnt lgkmcnt(2)
	v_cvt_pk_bf16_f32 v4, v16, v18
	s_waitcnt lgkmcnt(0)
	v_cvt_pk_bf16_f32 v5, v20, v24
	v_lshl_add_u64 v[6:7], v[22:23], 0, v[42:43]
	global_store_dwordx4 v[6:7], v[2:5], off
	v_or_b32_e32 v6, s10, v90
	v_mul_u32_u24_e32 v6, 0xb00, v6
	v_lshlrev_b32_e32 v42, 1, v6
	v_cvt_pk_bf16_f32 v2, v9, v11
	v_cvt_pk_bf16_f32 v3, v13, v15
	v_cvt_pk_bf16_f32 v4, v17, v19
	v_cvt_pk_bf16_f32 v5, v21, v25
	v_lshl_add_u64 v[6:7], v[22:23], 0, v[42:43]
	global_store_dwordx4 v[6:7], v[2:5], off
	s_waitcnt lgkmcnt(0)

.LBB0_37:
	s_andn2_b64 vcc, exec, s[10:11]
	s_cbranch_vccnz .LBB0_39
	s_load_dwordx2 s[10:11], s[70:71], 0x30
	s_and_b64 s[8:9], s[8:9], exec
	s_sext_i32_i16 s8, s13
	s_cselect_b32 s9, 0x1600000, 0
	s_mulk_i32 s8, 0xba3
	s_waitcnt lgkmcnt(0)
	s_add_u32 s46, s10, s9
	s_addc_u32 s47, s11, 0
	s_lshr_b32 s9, s8, 31
	s_ashr_i32 s8, s8, 19
	s_add_i32 s8, s8, s9
	s_mul_i32 s9, s8, 0xb0
	s_sub_i32 s10, s13, s9
	s_sext_i32_i16 s9, s10
	s_and_b32 s11, s9, 3
	s_bitcmp0_b32 s10, 2
	s_cselect_b32 s10, 0, 0x58
	s_lshr_b32 s13, s9, 1
	s_and_b32 s13, s13, 0x7fffffc
	s_add_i32 s10, s10, s13
	s_or_b32 s10, s10, s11
	s_lshl_b32 s10, s10, 5
	s_ashr_i32 s11, s10, 31
	s_lshl_b32 s8, s8, 6
	s_lshl_b64 s[10:11], s[10:11], 2
	v_or_b32_e32 v4, s8, v45
	s_add_u32 s10, s46, s10
	s_addc_u32 s11, s47, s11
	v_mov_b32_e32 v57, v43
	v_mul_i32_i24_e32 v4, 0x1600, v4
	v_lshl_add_u64 v[2:3], s[10:11], 0, v[56:57]
	v_ashrrev_i32_e32 v5, 31, v4
	v_lshl_add_u64 v[2:3], v[4:5], 2, v[2:3]
	v_add_co_u32_e32 v4, vcc, s0, v2
	s_lshl_b32 s10, s9, 5
	s_nop 0
	v_addc_co_u32_e32 v5, vcc, 0, v3, vcc
	v_add_co_u32_e32 v6, vcc, s33, v2
	s_ashr_i32 s9, s8, 31
	s_nop 0
	v_addc_co_u32_e32 v7, vcc, 0, v3, vcc
	v_add_co_u32_e32 v8, vcc, s58, v2
	s_lshl_b64 s[8:9], s[8:9], 1
	s_nop 0
	v_addc_co_u32_e32 v9, vcc, 0, v3, vcc
	v_add_co_u32_e32 v10, vcc, s44, v2
	s_add_u32 s8, s6, s8
	s_nop 0
	v_addc_co_u32_e32 v11, vcc, 0, v3, vcc
	v_add_co_u32_e32 v12, vcc, s1, v2
	s_addc_u32 s9, s12, s9
	s_nop 0
	v_addc_co_u32_e32 v13, vcc, 0, v3, vcc
	v_add_co_u32_e32 v14, vcc, s61, v2
	s_nop 1
	v_addc_co_u32_e32 v15, vcc, 0, v3, vcc
	v_add_co_u32_e32 v16, vcc, s72, v2
	s_nop 1
	v_addc_co_u32_e32 v17, vcc, 0, v3, vcc
	global_load_dword v20, v[2:3], off nt
	global_load_dword v21, v[4:5], off nt
	global_load_dword v22, v[6:7], off nt
	global_load_dword v23, v[8:9], off nt
	global_load_dword v24, v[10:11], off nt
	global_load_dword v25, v[12:13], off nt
	global_load_dword v26, v[14:15], off nt
	global_load_dword v27, v[16:17], off nt
	v_add_co_u32_e32 v4, vcc, s73, v2
	s_nop 1
	v_addc_co_u32_e32 v5, vcc, 0, v3, vcc
	v_add_co_u32_e32 v6, vcc, s74, v2
	s_nop 1
	v_addc_co_u32_e32 v7, vcc, 0, v3, vcc
	v_add_co_u32_e32 v8, vcc, s75, v2
	s_nop 1
	v_addc_co_u32_e32 v9, vcc, 0, v3, vcc
	v_add_co_u32_e32 v10, vcc, s76, v2
	s_nop 1
	v_addc_co_u32_e32 v11, vcc, 0, v3, vcc
	v_add_co_u32_e32 v12, vcc, s69, v2
	s_nop 1
	v_addc_co_u32_e32 v13, vcc, 0, v3, vcc
	v_add_co_u32_e32 v14, vcc, s77, v2
	s_nop 1
	v_addc_co_u32_e32 v15, vcc, 0, v3, vcc
	v_add_co_u32_e32 v16, vcc, s79, v2
	s_nop 1
	v_addc_co_u32_e32 v17, vcc, 0, v3, vcc
	v_add_co_u32_e32 v18, vcc, s80, v2
	s_nop 1
	v_addc_co_u32_e32 v19, vcc, 0, v3, vcc
	global_load_dword v28, v[4:5], off nt
	global_load_dword v29, v[6:7], off nt
	global_load_dword v30, v[8:9], off nt
	global_load_dword v31, v[10:11], off nt
	global_load_dword v32, v[12:13], off nt
	global_load_dword v33, v[14:15], off nt
	global_load_dword v34, v[16:17], off nt
	global_load_dword v35, v[18:19], off nt
	v_add_co_u32_e32 v4, vcc, s81, v2
	s_nop 1
	v_addc_co_u32_e32 v5, vcc, 0, v3, vcc
	v_add_co_u32_e32 v6, vcc, s82, v2
	s_nop 1
	v_addc_co_u32_e32 v7, vcc, 0, v3, vcc
	v_add_co_u32_e32 v8, vcc, s83, v2
	s_nop 1
	v_addc_co_u32_e32 v9, vcc, 0, v3, vcc
	v_add_co_u32_e32 v10, vcc, s84, v2
	s_nop 1
	v_addc_co_u32_e32 v11, vcc, 0, v3, vcc
	v_add_co_u32_e32 v12, vcc, s85, v2
	s_nop 1
	v_addc_co_u32_e32 v13, vcc, 0, v3, vcc
	v_add_co_u32_e32 v14, vcc, s86, v2
	s_nop 1
	v_addc_co_u32_e32 v15, vcc, 0, v3, vcc
	v_add_co_u32_e32 v16, vcc, s87, v2
	s_nop 1
	v_addc_co_u32_e32 v17, vcc, 0, v3, vcc
	v_add_co_u32_e32 v18, vcc, s88, v2
	s_nop 1
	v_addc_co_u32_e32 v19, vcc, 0, v3, vcc
	global_load_dword v36, v[4:5], off nt
	global_load_dword v37, v[6:7], off nt
	global_load_dword v38, v[8:9], off nt
	global_load_dword v39, v[10:11], off nt
	global_load_dword v40, v[12:13], off nt
	global_load_dword v41, v[14:15], off nt
	global_load_dword v42, v[16:17], off nt
	s_nop 0
	global_load_dword v18, v[18:19], off nt
	v_add_co_u32_e32 v4, vcc, s89, v2
	s_nop 1
	v_addc_co_u32_e32 v5, vcc, 0, v3, vcc
	v_add_co_u32_e32 v6, vcc, s90, v2
	s_nop 1
	v_addc_co_u32_e32 v7, vcc, 0, v3, vcc
	v_add_co_u32_e32 v8, vcc, s91, v2
	s_nop 1
	v_addc_co_u32_e32 v9, vcc, 0, v3, vcc
	v_add_co_u32_e32 v10, vcc, s92, v2
	s_nop 1
	v_addc_co_u32_e32 v11, vcc, 0, v3, vcc
	v_add_co_u32_e32 v12, vcc, s93, v2
	s_nop 1
	v_addc_co_u32_e32 v13, vcc, 0, v3, vcc
	v_add_co_u32_e32 v14, vcc, s94, v2
	s_nop 1
	v_addc_co_u32_e32 v15, vcc, 0, v3, vcc
	v_add_co_u32_e32 v16, vcc, s95, v2
	s_nop 1
	v_addc_co_u32_e32 v17, vcc, 0, v3, vcc
	v_add_co_u32_e32 v2, vcc, s96, v2
	s_nop 1
	v_addc_co_u32_e32 v3, vcc, 0, v3, vcc
	global_load_dword v4, v[4:5], off nt
	s_nop 0
	global_load_dword v5, v[6:7], off nt
	s_nop 0
	global_load_dword v6, v[8:9], off nt
	global_load_dword v7, v[10:11], off nt
	s_nop 0
	global_load_dword v8, v[12:13], off nt
	global_load_dword v9, v[14:15], off nt
	global_load_dword v10, v[16:17], off nt
	s_nop 0
	global_load_dword v2, v[2:3], off nt
	s_waitcnt vmcnt(30)
	ds_write2_b32 v55, v20, v21 offset1:66
	s_waitcnt vmcnt(28)
	ds_write2_b32 v55, v22, v23 offset0:132 offset1:198
	s_waitcnt vmcnt(26)
	ds_write2_b32 v92, v24, v25 offset0:8 offset1:74
	s_waitcnt vmcnt(24)
	ds_write2_b32 v92, v26, v27 offset0:140 offset1:206
	s_waitcnt vmcnt(22)
	ds_write2_b32 v93, v28, v29 offset0:16 offset1:82
	s_waitcnt vmcnt(20)
	ds_write2_b32 v93, v30, v31 offset0:148 offset1:214
	s_waitcnt vmcnt(18)
	ds_write2_b32 v94, v32, v33 offset0:24 offset1:90
	s_waitcnt vmcnt(16)
	ds_write2_b32 v94, v34, v35 offset0:156 offset1:222
	s_waitcnt vmcnt(14)
	ds_write2_b32 v95, v36, v37 offset0:32 offset1:98
	s_waitcnt vmcnt(12)
	ds_write2_b32 v95, v38, v39 offset0:164 offset1:230
	s_waitcnt vmcnt(10)
	ds_write2_b32 v96, v40, v41 offset0:40 offset1:106
	s_waitcnt vmcnt(8)
	ds_write2_b32 v96, v42, v18 offset0:172 offset1:238
	s_waitcnt vmcnt(6)
	ds_write2_b32 v97, v4, v5 offset0:48 offset1:114
	s_waitcnt vmcnt(4)
	ds_write2_b32 v97, v6, v7 offset0:180 offset1:246
	s_waitcnt vmcnt(2)
	ds_write2_b32 v98, v8, v9 offset0:56 offset1:122
	s_waitcnt vmcnt(0)
	ds_write2_b32 v98, v10, v2 offset0:188 offset1:254
	s_waitcnt lgkmcnt(0)
	ds_read2_b32 v[6:7], v85 offset0:33 offset1:41
	ds_read2_b32 v[8:9], v85 offset1:8
	ds_read2_b32 v[10:11], v85 offset0:66 offset1:74
	ds_read2_b32 v[12:13], v85 offset0:99 offset1:107
	ds_read2_b32 v[14:15], v85 offset0:132 offset1:140
	ds_read2_b32 v[16:17], v85 offset0:165 offset1:173
	ds_read2_b32 v[18:19], v85 offset0:198 offset1:206
	ds_read2_b32 v[20:21], v85 offset0:231 offset1:239
	v_or_b32_e32 v24, s10, v81
	v_lshlrev_b32_e32 v42, 1, v44
	v_ashrrev_i32_e32 v25, 31, v24
	v_lshl_add_u64 v[22:23], s[8:9], 0, v[42:43]
	v_lshlrev_b64 v[24:25], 11, v[24:25]
	s_waitcnt lgkmcnt(6)
	v_cvt_pk_bf16_f32 v2, v8, v6
	s_waitcnt lgkmcnt(4)
	v_cvt_pk_bf16_f32 v3, v10, v12
	s_waitcnt lgkmcnt(2)
	v_cvt_pk_bf16_f32 v4, v14, v16
	s_waitcnt lgkmcnt(0)
	v_cvt_pk_bf16_f32 v5, v18, v20
	v_lshl_add_u64 v[24:25], v[22:23], 0, v[24:25]
	v_or_b32_e32 v6, s10, v88
	global_store_dwordx4 v[24:25], v[2:5], off
	s_nop 1
	v_cvt_pk_bf16_f32 v2, v9, v7
	v_ashrrev_i32_e32 v7, 31, v6
	v_cvt_pk_bf16_f32 v3, v11, v13
	v_cvt_pk_bf16_f32 v4, v15, v17
	v_cvt_pk_bf16_f32 v5, v19, v21
	v_lshlrev_b64 v[6:7], 11, v[6:7]
	ds_read2_b32 v[8:9], v85 offset0:49 offset1:57
	ds_read2_b32 v[10:11], v85 offset0:16 offset1:24
	ds_read2_b32 v[12:13], v85 offset0:82 offset1:90
	ds_read2_b32 v[14:15], v85 offset0:115 offset1:123
	ds_read2_b32 v[16:17], v85 offset0:148 offset1:156
	ds_read2_b32 v[18:19], v85 offset0:181 offset1:189
	ds_read2_b32 v[20:21], v85 offset0:214 offset1:222
	ds_read2_b32 v[24:25], v85 offset0:247 offset1:255
	v_lshl_add_u64 v[6:7], v[22:23], 0, v[6:7]
	global_store_dwordx4 v[6:7], v[2:5], off
	v_or_b32_e32 v6, s10, v89
	v_ashrrev_i32_e32 v7, 31, v6
	v_lshlrev_b64 v[6:7], 11, v[6:7]
	s_waitcnt lgkmcnt(6)
	v_cvt_pk_bf16_f32 v2, v10, v8
	s_waitcnt lgkmcnt(4)
	v_cvt_pk_bf16_f32 v3, v12, v14
	s_waitcnt lgkmcnt(2)
	v_cvt_pk_bf16_f32 v4, v16, v18
	s_waitcnt lgkmcnt(0)
	v_cvt_pk_bf16_f32 v5, v20, v24
	v_lshl_add_u64 v[6:7], v[22:23], 0, v[6:7]
	global_store_dwordx4 v[6:7], v[2:5], off
	v_or_b32_e32 v6, s10, v90
	v_ashrrev_i32_e32 v7, 31, v6
	v_lshlrev_b64 v[6:7], 11, v[6:7]
	v_cvt_pk_bf16_f32 v2, v11, v9
	v_cvt_pk_bf16_f32 v3, v13, v15
	v_cvt_pk_bf16_f32 v4, v17, v19
	v_cvt_pk_bf16_f32 v5, v21, v25
	v_lshl_add_u64 v[6:7], v[22:23], 0, v[6:7]
	global_store_dwordx4 v[6:7], v[2:5], off
	s_waitcnt lgkmcnt(0)

.LBB0_41:
	s_mul_hi_i32 s6, s14, 0x38e38e39
	s_lshr_b32 s46, s6, 31
	s_ashr_i32 s6, s6, 4
	s_load_dwordx2 s[12:13], s[70:71], 0x8
	s_load_dwordx4 s[8:11], s[70:71], 0x18
	s_add_i32 s6, s6, s46
	s_lshl_b32 s97, s6, 6
	v_or_b32_e32 v2, s97, v1
	v_ashrrev_i32_e32 v3, 31, v2
	v_lshlrev_b64 v[4:5], 2, v[2:3]
	v_add_u32_e32 v8, 0x400, v2
	v_add_u32_e32 v10, 0x800, v2
	v_add_u32_e32 v2, 0xc00, v2
	s_waitcnt lgkmcnt(0)
	v_lshl_add_u64 v[6:7], s[8:9], 0, v[4:5]
	v_lshl_add_u64 v[4:5], s[12:13], 0, v[4:5]
	v_ashrrev_i32_e32 v9, 31, v8
	v_ashrrev_i32_e32 v11, 31, v10
	v_ashrrev_i32_e32 v3, 31, v2
	v_lshl_add_u64 v[8:9], v[8:9], 2, s[12:13]
	v_lshl_add_u64 v[10:11], v[10:11], 2, s[12:13]
	v_lshl_add_u64 v[2:3], v[2:3], 2, s[12:13]
	global_load_dword v15, v[4:5], off nt
	global_load_dword v16, v[8:9], off nt
	global_load_dword v17, v[10:11], off nt
	global_load_dword v18, v[2:3], off nt
	global_load_dword v19, v[6:7], off nt
	s_mul_i32 s8, s6, 0x48
	s_sub_i32 s46, s14, s8
	s_mul_i32 s47, s46, 57
	s_lshl_b32 s8, s46, 8
	s_mul_i32 s46, s46, 0xe3900
	s_sext_i32_i16 s98, s47
	s_bfe_u32 s47, s47, 0x1000f
	s_lshr_b32 vcc_lo, s46, 31
	s_lshr_b32 s46, s46, 25
	s_ashr_i32 s98, s98, 11
	s_add_i32 vcc_lo, s46, vcc_lo
	s_add_i32 s46, s98, s47
	s_mulk_i32 vcc_lo, 0x2400
	s_bfe_i64 s[46:47], s[46:47], 0x100000
	s_ashr_i32 s99, s97, 31
	s_sub_i32 s98, s8, vcc_lo
	s_lshl_b64 s[46:47], s[46:47], 10
	s_add_u32 s46, s46, s97
	s_addc_u32 s47, s47, s99
	s_mul_hi_u32 s97, s46, 0x9000
	s_mul_i32 s47, s47, 0x9000
	s_mul_i32 s46, s46, 0x9000
	s_add_i32 s97, s97, s47
	s_add_u32 s46, s10, s46
	s_addc_u32 s47, s11, s97
	s_bfe_i64 s[10:11], s[98:99], 0x100000
	s_lshl_b64 s[10:11], s[10:11], 2
	s_add_u32 s10, s46, s10
	v_lshlrev_b32_e32 v42, 2, v54
	v_mov_b32_e32 v10, 0
	s_addc_u32 s11, s47, s11
	s_mov_b64 s[12:13], 0
	s_mov_b32 s9, s15
	v_mov_b32_e32 v11, v10
	v_mov_b32_e32 v12, v10
	v_mov_b32_e32 v13, v10
	v_mov_b32_e32 v2, v10
	v_mov_b32_e32 v3, v10
	v_mov_b32_e32 v4, v10
	v_mov_b32_e32 v5, v10
	v_mov_b32_e32 v6, v10
	v_mov_b32_e32 v7, v10
	v_mov_b32_e32 v8, v10
	v_mov_b32_e32 v9, v10
	v_mov_b32_e32 v14, v10
	v_lshl_add_u64 v[58:59], s[10:11], 0, v[42:43]
	s_waitcnt vmcnt(4)
	v_mul_f32_e32 v20, 0xbfb8aa3b, v15
	s_waitcnt vmcnt(3)
	v_mul_f32_e32 v21, 0xbfb8aa3b, v16
	s_waitcnt vmcnt(2)
	v_mul_f32_e32 v22, 0xbfb8aa3b, v17
	s_waitcnt vmcnt(1)
	v_mul_f32_e32 v23, 0xbfb8aa3b, v18
	s_waitcnt vmcnt(0)
	v_mul_f32_e32 v24, 0xbfb8aa3b, v19
	v_exp_f32_e32 v20, v20
	v_exp_f32_e32 v21, v21
	v_exp_f32_e32 v22, v22
	v_exp_f32_e32 v23, v23
	v_exp_f32_e32 v24, v24
	v_add_f32_e32 v20, 1.0, v20
	v_add_f32_e32 v21, 1.0, v21
	v_add_f32_e32 v22, 1.0, v22
	v_add_f32_e32 v23, 1.0, v23
	v_add_f32_e32 v24, 1.0, v24
	v_rcp_f32_e32 v20, v20
	v_rcp_f32_e32 v21, v21
	v_rcp_f32_e32 v22, v22
	v_rcp_f32_e32 v23, v23
	v_rcp_f32_e32 v24, v24
	v_mul_f32_e32 v15, v15, v20
	v_mul_f32_e32 v16, v16, v21
	v_mul_f32_e32 v17, v17, v22
	v_mul_f32_e32 v18, v18, v23
	v_mul_f32_e32 v19, v19, v24
	ds_write2st64_b32 v91, v15, v16 offset1:1
	ds_write2st64_b32 v91, v17, v18 offset0:2 offset1:3
	ds_write_b32 v91, v19 offset:1024
	s_waitcnt lgkmcnt(0)
	v_mov_b32_e32 v15, v10
	v_mov_b32_e32 v16, v10
	v_mov_b32_e32 v17, v10
	v_mov_b32_e32 v18, v10
	v_mov_b32_e32 v19, v10
	v_mov_b32_e32 v20, v10
	v_mov_b32_e32 v21, v10
.LBB0_42:
	v_lshl_add_u64 v[38:39], v[58:59], 0, s[12:13]
	global_load_dwordx4 v[22:25], v[38:39], off nt
	v_mov_b32_e32 v57, s9
	ds_read_b128 v[26:29], v57
	ds_read_b128 v[30:33], v57 offset:16
	ds_read_b128 v[34:37], v57 offset:1024
	ds_read_b128 v[60:63], v57 offset:256
	ds_read_b128 v[64:67], v57 offset:272
	ds_read_b128 v[68:71], v57 offset:512
	ds_read_b128 v[72:75], v57 offset:528
	ds_read_b128 v[76:79], v57 offset:768
	ds_read_b128 v[100:103], v57 offset:784
	s_mov_b32 s10, 0x75000
	s_add_u32 s12, s12, 0x90000
	s_addc_u32 s13, s13, 0
	s_add_i32 s9, s9, 64
	s_cmp_lg_u32 s12, 0x240000
	s_waitcnt vmcnt(0) lgkmcnt(8)
	v_pk_fma_f32 v[82:83], v[22:23], v[26:27], v[10:11] op_sel_hi:[1,0,1]
	s_waitcnt lgkmcnt(5)
	v_pk_fma_f32 v[18:19], v[22:23], v[60:61], v[18:19] op_sel_hi:[1,0,1]
	s_waitcnt lgkmcnt(3)
	v_pk_fma_f32 v[86:87], v[22:23], v[68:69], v[14:15] op_sel_hi:[1,0,1]
	s_waitcnt lgkmcnt(1)
	v_pk_fma_f32 v[6:7], v[22:23], v[76:77], v[6:7] op_sel_hi:[1,0,1]
	v_pk_fma_f32 v[22:23], v[22:23], v[34:35], v[2:3] op_sel_hi:[1,0,1]
	v_add_co_u32_e32 v2, vcc, s56, v38
	v_pk_fma_f32 v[40:41], v[24:25], v[26:27], v[12:13] op_sel_hi:[1,0,1]
	s_nop 0
	v_addc_co_u32_e32 v3, vcc, 0, v39, vcc
	v_add_co_u32_e32 v12, vcc, s30, v38
	v_pk_fma_f32 v[20:21], v[24:25], v[60:61], v[20:21] op_sel_hi:[1,0,1]
	s_nop 0
	v_addc_co_u32_e32 v13, vcc, 0, v39, vcc
	v_pk_fma_f32 v[16:17], v[24:25], v[68:69], v[16:17] op_sel_hi:[1,0,1]
	v_pk_fma_f32 v[104:105], v[24:25], v[76:77], v[8:9] op_sel_hi:[1,0,1]
	ds_read_b128 v[8:11], v57 offset:1040
	v_pk_fma_f32 v[24:25], v[24:25], v[34:35], v[4:5] op_sel_hi:[1,0,1]
	global_load_dwordx4 v[2:5], v[2:3], off nt
	s_nop 0
	global_load_dwordx4 v[12:15], v[12:13], off nt
	s_waitcnt vmcnt(1)
	v_pk_fma_f32 v[82:83], v[2:3], v[26:27], v[82:83] op_sel:[0,1,0]
	v_pk_fma_f32 v[26:27], v[4:5], v[26:27], v[40:41] op_sel:[0,1,0]
	v_pk_fma_f32 v[18:19], v[2:3], v[60:61], v[18:19] op_sel:[0,1,0]
	v_pk_fma_f32 v[20:21], v[4:5], v[60:61], v[20:21] op_sel:[0,1,0]
	v_pk_fma_f32 v[16:17], v[4:5], v[68:69], v[16:17] op_sel:[0,1,0]
	v_pk_fma_f32 v[60:61], v[4:5], v[76:77], v[104:105] op_sel:[0,1,0]
	v_pk_fma_f32 v[4:5], v[4:5], v[34:35], v[24:25] op_sel:[0,1,0]
	v_pk_fma_f32 v[40:41], v[2:3], v[68:69], v[86:87] op_sel:[0,1,0]
	v_pk_fma_f32 v[6:7], v[2:3], v[76:77], v[6:7] op_sel:[0,1,0]
	v_pk_fma_f32 v[2:3], v[2:3], v[34:35], v[22:23] op_sel:[0,1,0]
	s_waitcnt vmcnt(0)
	v_pk_fma_f32 v[34:35], v[12:13], v[28:29], v[82:83] op_sel_hi:[1,0,1]
	v_pk_fma_f32 v[82:83], v[14:15], v[36:37], v[4:5] op_sel_hi:[1,0,1]
	v_add_co_u32_e32 v4, vcc, s57, v38
	v_pk_fma_f32 v[26:27], v[14:15], v[28:29], v[26:27] op_sel_hi:[1,0,1]
	s_nop 0
	v_addc_co_u32_e32 v5, vcc, 0, v39, vcc
	v_pk_fma_f32 v[20:21], v[14:15], v[62:63], v[20:21] op_sel_hi:[1,0,1]
	v_pk_fma_f32 v[68:69], v[12:13], v[62:63], v[18:19] op_sel_hi:[1,0,1]
	v_pk_fma_f32 v[76:77], v[14:15], v[70:71], v[16:17] op_sel_hi:[1,0,1]
	v_pk_fma_f32 v[40:41], v[12:13], v[70:71], v[40:41] op_sel_hi:[1,0,1]
	v_pk_fma_f32 v[60:61], v[14:15], v[78:79], v[60:61] op_sel_hi:[1,0,1]
	v_pk_fma_f32 v[6:7], v[12:13], v[78:79], v[6:7] op_sel_hi:[1,0,1]
	v_pk_fma_f32 v[86:87], v[12:13], v[36:37], v[2:3] op_sel_hi:[1,0,1]
	global_load_dwordx4 v[12:15], v[4:5], off nt
	v_add_co_u32_e32 v16, vcc, s40, v38
	v_mov_b32_e32 v28, v29
	s_nop 0
	v_addc_co_u32_e32 v17, vcc, 0, v39, vcc
	global_load_dwordx4 v[16:19], v[16:17], off nt
	v_mov_b32_e32 v2, v63
	v_mov_b32_e32 v36, v71
	v_mov_b32_e32 v70, v37
	v_mov_b32_e32 v62, v79
	ds_read_b128 v[22:25], v57 offset:32
	s_waitcnt vmcnt(1)
	v_pk_fma_f32 v[26:27], v[14:15], v[28:29], v[26:27] op_sel_hi:[1,0,1]
	v_pk_fma_f32 v[28:29], v[12:13], v[28:29], v[34:35] op_sel_hi:[1,0,1]
	v_pk_fma_f32 v[34:35], v[12:13], v[2:3], v[68:69] op_sel_hi:[1,0,1]
	v_pk_fma_f32 v[68:69], v[14:15], v[36:37], v[76:77] op_sel_hi:[1,0,1]
	v_pk_fma_f32 v[36:37], v[12:13], v[36:37], v[40:41] op_sel_hi:[1,0,1]
	v_add_co_u32_e32 v40, vcc, s59, v38
	v_pk_fma_f32 v[60:61], v[14:15], v[62:63], v[60:61] op_sel_hi:[1,0,1]
	s_nop 0
	v_addc_co_u32_e32 v41, vcc, 0, v39, vcc
	v_pk_fma_f32 v[6:7], v[12:13], v[62:63], v[6:7] op_sel_hi:[1,0,1]
	v_add_co_u32_e32 v62, vcc, s51, v38
	v_pk_fma_f32 v[20:21], v[14:15], v[2:3], v[20:21] op_sel_hi:[1,0,1]
	s_nop 0
	v_addc_co_u32_e32 v63, vcc, 0, v39, vcc
	v_pk_fma_f32 v[76:77], v[14:15], v[70:71], v[82:83] op_sel_hi:[1,0,1]
	v_pk_fma_f32 v[70:71], v[12:13], v[70:71], v[86:87] op_sel_hi:[1,0,1]
	global_load_dwordx4 v[12:15], v[40:41], off nt
	s_waitcnt vmcnt(1)
	v_pk_fma_f32 v[26:27], v[18:19], v[30:31], v[26:27] op_sel_hi:[1,0,1]
	v_pk_fma_f32 v[28:29], v[16:17], v[30:31], v[28:29] op_sel_hi:[1,0,1]
	v_pk_fma_f32 v[20:21], v[18:19], v[64:65], v[20:21] op_sel_hi:[1,0,1]
	v_pk_fma_f32 v[34:35], v[16:17], v[64:65], v[34:35] op_sel_hi:[1,0,1]
	v_pk_fma_f32 v[40:41], v[18:19], v[72:73], v[68:69] op_sel_hi:[1,0,1]
	v_pk_fma_f32 v[36:37], v[16:17], v[72:73], v[36:37] op_sel_hi:[1,0,1]
	s_waitcnt lgkmcnt(2)
	v_pk_fma_f32 v[60:61], v[18:19], v[100:101], v[60:61] op_sel_hi:[1,0,1]
	v_pk_fma_f32 v[6:7], v[16:17], v[100:101], v[6:7] op_sel_hi:[1,0,1]
	s_waitcnt lgkmcnt(1)
	v_pk_fma_f32 v[68:69], v[18:19], v[8:9], v[76:77] op_sel_hi:[1,0,1]
	v_pk_fma_f32 v[70:71], v[16:17], v[8:9], v[70:71] op_sel_hi:[1,0,1]
	global_load_dwordx4 v[16:19], v[62:63], off nt
	v_add_co_u32_e32 v78, vcc, s60, v38
	v_mov_b32_e32 v76, v75
	s_nop 0
	v_addc_co_u32_e32 v79, vcc, 0, v39, vcc
	v_add_co_u32_e32 v82, vcc, s62, v38
	ds_read_b128 v[2:5], v57 offset:48
	s_nop 0
	v_addc_co_u32_e32 v83, vcc, 0, v39, vcc
	s_waitcnt vmcnt(1)
	v_pk_fma_f32 v[62:63], v[14:15], v[30:31], v[26:27] op_sel:[0,1,0]
	v_pk_fma_f32 v[20:21], v[14:15], v[64:65], v[20:21] op_sel:[0,1,0]
	v_pk_fma_f32 v[40:41], v[14:15], v[72:73], v[40:41] op_sel:[0,1,0]
	v_pk_fma_f32 v[60:61], v[14:15], v[100:101], v[60:61] op_sel:[0,1,0]
	v_pk_fma_f32 v[14:15], v[14:15], v[8:9], v[68:69] op_sel:[0,1,0]
	v_pk_fma_f32 v[34:35], v[12:13], v[64:65], v[34:35] op_sel:[0,1,0]
	v_pk_fma_f32 v[8:9], v[12:13], v[8:9], v[70:71] op_sel:[0,1,0]
	v_pk_fma_f32 v[30:31], v[12:13], v[30:31], v[28:29] op_sel:[0,1,0]
	v_pk_fma_f32 v[36:37], v[12:13], v[72:73], v[36:37] op_sel:[0,1,0]
	v_pk_fma_f32 v[6:7], v[12:13], v[100:101], v[6:7] op_sel:[0,1,0]
	ds_read_b128 v[26:29], v57 offset:288
	s_waitcnt vmcnt(0)
	v_pk_fma_f32 v[64:65], v[18:19], v[32:33], v[62:63] op_sel_hi:[1,0,1]
	v_pk_fma_f32 v[70:71], v[18:19], v[66:67], v[20:21] op_sel_hi:[1,0,1]
	v_pk_fma_f32 v[40:41], v[18:19], v[74:75], v[40:41] op_sel_hi:[1,0,1]
	v_pk_fma_f32 v[86:87], v[18:19], v[102:103], v[60:61] op_sel_hi:[1,0,1]
	v_pk_fma_f32 v[104:105], v[18:19], v[10:11], v[14:15] op_sel_hi:[1,0,1]
	global_load_dwordx4 v[18:21], v[78:79], off nt
	global_load_dwordx4 v[60:63], v[82:83], off nt
	v_mov_b32_e32 v12, v33
	v_pk_fma_f32 v[68:69], v[16:17], v[32:33], v[30:31] op_sel_hi:[1,0,1]
	ds_read_b128 v[30:33], v57 offset:544
	v_pk_fma_f32 v[72:73], v[16:17], v[66:67], v[34:35] op_sel_hi:[1,0,1]
	v_mov_b32_e32 v66, v67
	v_pk_fma_f32 v[74:75], v[16:17], v[74:75], v[36:37] op_sel_hi:[1,0,1]
	ds_read_b128 v[34:37], v57 offset:800
	v_pk_fma_f32 v[100:101], v[16:17], v[102:103], v[6:7] op_sel_hi:[1,0,1]
	v_pk_fma_f32 v[106:107], v[16:17], v[10:11], v[8:9] op_sel_hi:[1,0,1]
	v_mov_b32_e32 v14, v103
	v_mov_b32_e32 v78, v11
	ds_read_b128 v[6:9], v57 offset:304
	s_waitcnt vmcnt(1)
	v_pk_fma_f32 v[82:83], v[20:21], v[12:13], v[64:65] op_sel_hi:[1,0,1]
	v_pk_fma_f32 v[68:69], v[18:19], v[12:13], v[68:69] op_sel_hi:[1,0,1]
	v_pk_fma_f32 v[70:71], v[20:21], v[66:67], v[70:71] op_sel_hi:[1,0,1]
	v_pk_fma_f32 v[72:73], v[18:19], v[66:67], v[72:73] op_sel_hi:[1,0,1]
	ds_read_b128 v[10:13], v57 offset:560
	v_pk_fma_f32 v[40:41], v[20:21], v[76:77], v[40:41] op_sel_hi:[1,0,1]
	v_pk_fma_f32 v[74:75], v[18:19], v[76:77], v[74:75] op_sel_hi:[1,0,1]
	v_pk_fma_f32 v[76:77], v[20:21], v[14:15], v[86:87] op_sel_hi:[1,0,1]
	v_pk_fma_f32 v[86:87], v[18:19], v[14:15], v[100:101] op_sel_hi:[1,0,1]
	ds_read_b128 v[14:17], v57 offset:816
	v_pk_fma_f32 v[100:101], v[20:21], v[78:79], v[104:105] op_sel_hi:[1,0,1]
	v_pk_fma_f32 v[78:79], v[18:19], v[78:79], v[106:107] op_sel_hi:[1,0,1]
	ds_read_b128 v[64:67], v57 offset:1056
	ds_read_b128 v[18:21], v57 offset:1072
	s_waitcnt vmcnt(0) lgkmcnt(9)
	v_pk_fma_f32 v[68:69], v[60:61], v[22:23], v[68:69] op_sel_hi:[1,0,1]
	s_waitcnt lgkmcnt(7)
	v_pk_fma_f32 v[72:73], v[60:61], v[26:27], v[72:73] op_sel_hi:[1,0,1]
	s_waitcnt lgkmcnt(6)
	v_pk_fma_f32 v[74:75], v[60:61], v[30:31], v[74:75] op_sel_hi:[1,0,1]
	s_waitcnt lgkmcnt(5)
	v_pk_fma_f32 v[86:87], v[60:61], v[34:35], v[86:87] op_sel_hi:[1,0,1]
	s_waitcnt lgkmcnt(1)
	v_pk_fma_f32 v[78:79], v[60:61], v[64:65], v[78:79] op_sel_hi:[1,0,1]
	v_add_co_u32_e32 v60, vcc, s64, v38
	v_pk_fma_f32 v[104:105], v[62:63], v[64:65], v[100:101] op_sel_hi:[1,0,1]
	s_nop 0
	v_addc_co_u32_e32 v61, vcc, 0, v39, vcc
	v_add_co_u32_e32 v100, vcc, s66, v38
	v_pk_fma_f32 v[82:83], v[62:63], v[22:23], v[82:83] op_sel_hi:[1,0,1]
	s_nop 0
	v_addc_co_u32_e32 v101, vcc, 0, v39, vcc
	v_pk_fma_f32 v[70:71], v[62:63], v[26:27], v[70:71] op_sel_hi:[1,0,1]
	v_pk_fma_f32 v[40:41], v[62:63], v[30:31], v[40:41] op_sel_hi:[1,0,1]
	v_pk_fma_f32 v[76:77], v[62:63], v[34:35], v[76:77] op_sel_hi:[1,0,1]
	global_load_dwordx4 v[60:63], v[60:61], off nt
	s_nop 0
	global_load_dwordx4 v[100:103], v[100:101], off nt
	v_mov_b32_e32 v84, v33
	v_mov_b32_e32 v80, v67
	s_waitcnt vmcnt(1)
	v_pk_fma_f32 v[82:83], v[62:63], v[22:23], v[82:83] op_sel:[0,1,0]
	v_pk_fma_f32 v[22:23], v[60:61], v[22:23], v[68:69] op_sel:[0,1,0]
	v_pk_fma_f32 v[68:69], v[62:63], v[26:27], v[70:71] op_sel:[0,1,0]
	v_pk_fma_f32 v[26:27], v[60:61], v[26:27], v[72:73] op_sel:[0,1,0]
	v_pk_fma_f32 v[40:41], v[62:63], v[30:31], v[40:41] op_sel:[0,1,0]
	v_pk_fma_f32 v[70:71], v[62:63], v[34:35], v[76:77] op_sel:[0,1,0]
	v_pk_fma_f32 v[62:63], v[62:63], v[64:65], v[104:105] op_sel:[0,1,0]
	s_waitcnt vmcnt(0)
	v_pk_fma_f32 v[104:105], v[100:101], v[28:29], v[26:27] op_sel_hi:[1,0,1]
	v_add_co_u32_e32 v26, vcc, s74, v38
	v_pk_fma_f32 v[30:31], v[60:61], v[30:31], v[74:75] op_sel:[0,1,0]
	s_nop 0
	v_addc_co_u32_e32 v27, vcc, 0, v39, vcc
	v_pk_fma_f32 v[34:35], v[60:61], v[34:35], v[86:87] op_sel:[0,1,0]
	v_pk_fma_f32 v[60:61], v[60:61], v[64:65], v[78:79] op_sel:[0,1,0]
	v_pk_fma_f32 v[78:79], v[100:101], v[32:33], v[30:31] op_sel_hi:[1,0,1]
	v_add_co_u32_e32 v30, vcc, s67, v38
	v_pk_fma_f32 v[72:73], v[102:103], v[36:37], v[70:71] op_sel_hi:[1,0,1]
	s_nop 0
	v_addc_co_u32_e32 v31, vcc, 0, v39, vcc
	v_pk_fma_f32 v[70:71], v[100:101], v[66:67], v[60:61] op_sel_hi:[1,0,1]
	v_add_co_u32_e32 v60, vcc, s10, v38
	v_pk_fma_f32 v[22:23], v[100:101], v[24:25], v[22:23] op_sel_hi:[1,0,1]
	s_nop 0
	v_addc_co_u32_e32 v61, vcc, 0, v39, vcc
	v_pk_fma_f32 v[74:75], v[100:101], v[36:37], v[34:35] op_sel_hi:[1,0,1]
	v_add_co_u32_e32 v100, vcc, s68, v38
	s_mov_b32 s10, 0x87000
	s_nop 0
	v_addc_co_u32_e32 v101, vcc, 0, v39, vcc
	v_pk_fma_f32 v[64:65], v[102:103], v[24:25], v[82:83] op_sel_hi:[1,0,1]
	v_pk_fma_f32 v[86:87], v[102:103], v[28:29], v[68:69] op_sel_hi:[1,0,1]
	v_pk_fma_f32 v[76:77], v[102:103], v[32:33], v[40:41] op_sel_hi:[1,0,1]
	v_pk_fma_f32 v[68:69], v[102:103], v[66:67], v[62:63] op_sel_hi:[1,0,1]
	v_add_co_u32_e32 v102, vcc, s10, v38
	v_mov_b32_e32 v82, v37
	s_nop 0
	v_addc_co_u32_e32 v103, vcc, 0, v39, vcc
	global_load_dwordx4 v[38:41], v[26:27], off nt
	global_load_dwordx4 v[34:37], v[30:31], off nt
	v_mov_b32_e32 v24, v25
	global_load_dwordx4 v[30:33], v[60:61], off nt
	v_mov_b32_e32 v66, v29
	global_load_dwordx4 v[26:29], v[100:101], off nt
	s_waitcnt vmcnt(3)
	v_pk_fma_f32 v[60:61], v[40:41], v[24:25], v[64:65] op_sel_hi:[1,0,1]
	v_pk_fma_f32 v[62:63], v[38:39], v[24:25], v[22:23] op_sel_hi:[1,0,1]
	global_load_dwordx4 v[22:25], v[102:103], off nt
	v_pk_fma_f32 v[64:65], v[40:41], v[66:67], v[86:87] op_sel_hi:[1,0,1]
	v_pk_fma_f32 v[66:67], v[38:39], v[66:67], v[104:105] op_sel_hi:[1,0,1]
	v_pk_fma_f32 v[76:77], v[40:41], v[84:85], v[76:77] op_sel_hi:[1,0,1]
	v_pk_fma_f32 v[78:79], v[38:39], v[84:85], v[78:79] op_sel_hi:[1,0,1]
	v_pk_fma_f32 v[86:87], v[40:41], v[82:83], v[72:73] op_sel_hi:[1,0,1]
	v_pk_fma_f32 v[74:75], v[38:39], v[82:83], v[74:75] op_sel_hi:[1,0,1]
	v_pk_fma_f32 v[82:83], v[40:41], v[80:81], v[68:69] op_sel_hi:[1,0,1]
	v_pk_fma_f32 v[70:71], v[38:39], v[80:81], v[70:71] op_sel_hi:[1,0,1]
	s_waitcnt vmcnt(3)
	v_pk_fma_f32 v[60:61], v[36:37], v[2:3], v[60:61] op_sel_hi:[1,0,1]
	v_pk_fma_f32 v[62:63], v[34:35], v[2:3], v[62:63] op_sel_hi:[1,0,1]
	v_pk_fma_f32 v[64:65], v[36:37], v[6:7], v[64:65] op_sel_hi:[1,0,1]
	v_pk_fma_f32 v[66:67], v[34:35], v[6:7], v[66:67] op_sel_hi:[1,0,1]
	v_pk_fma_f32 v[76:77], v[36:37], v[10:11], v[76:77] op_sel_hi:[1,0,1]
	v_pk_fma_f32 v[78:79], v[34:35], v[10:11], v[78:79] op_sel_hi:[1,0,1]
	v_pk_fma_f32 v[86:87], v[36:37], v[14:15], v[86:87] op_sel_hi:[1,0,1]
	v_pk_fma_f32 v[74:75], v[34:35], v[14:15], v[74:75] op_sel_hi:[1,0,1]
	s_waitcnt lgkmcnt(0)
	v_pk_fma_f32 v[36:37], v[36:37], v[18:19], v[82:83] op_sel_hi:[1,0,1]
	v_pk_fma_f32 v[34:35], v[34:35], v[18:19], v[70:71] op_sel_hi:[1,0,1]
	s_waitcnt vmcnt(2)
	v_pk_fma_f32 v[60:61], v[32:33], v[2:3], v[60:61] op_sel:[0,1,0]
	v_pk_fma_f32 v[2:3], v[30:31], v[2:3], v[62:63] op_sel:[0,1,0]
	v_pk_fma_f32 v[62:63], v[32:33], v[6:7], v[64:65] op_sel:[0,1,0]
	v_pk_fma_f32 v[6:7], v[30:31], v[6:7], v[66:67] op_sel:[0,1,0]
	v_pk_fma_f32 v[64:65], v[32:33], v[10:11], v[76:77] op_sel:[0,1,0]
	v_pk_fma_f32 v[10:11], v[30:31], v[10:11], v[78:79] op_sel:[0,1,0]
	v_pk_fma_f32 v[66:67], v[32:33], v[14:15], v[86:87] op_sel:[0,1,0]
	v_pk_fma_f32 v[14:15], v[30:31], v[14:15], v[74:75] op_sel:[0,1,0]
	v_pk_fma_f32 v[32:33], v[32:33], v[18:19], v[36:37] op_sel:[0,1,0]
	v_pk_fma_f32 v[18:19], v[30:31], v[18:19], v[34:35] op_sel:[0,1,0]
	v_mov_b32_e32 v84, v5
	v_mov_b32_e32 v72, v9
	v_mov_b32_e32 v38, v13
	v_mov_b32_e32 v40, v17
	v_mov_b32_e32 v68, v21
	s_waitcnt vmcnt(1)
	v_pk_fma_f32 v[30:31], v[28:29], v[4:5], v[60:61] op_sel_hi:[1,0,1]
	v_pk_fma_f32 v[2:3], v[26:27], v[4:5], v[2:3] op_sel_hi:[1,0,1]
	v_pk_fma_f32 v[4:5], v[28:29], v[8:9], v[62:63] op_sel_hi:[1,0,1]
	v_pk_fma_f32 v[6:7], v[26:27], v[8:9], v[6:7] op_sel_hi:[1,0,1]
	v_pk_fma_f32 v[8:9], v[28:29], v[12:13], v[64:65] op_sel_hi:[1,0,1]
	v_pk_fma_f32 v[34:35], v[26:27], v[12:13], v[10:11] op_sel_hi:[1,0,1]
	v_pk_fma_f32 v[36:37], v[28:29], v[16:17], v[66:67] op_sel_hi:[1,0,1]
	v_pk_fma_f32 v[60:61], v[26:27], v[16:17], v[14:15] op_sel_hi:[1,0,1]
	v_pk_fma_f32 v[28:29], v[28:29], v[20:21], v[32:33] op_sel_hi:[1,0,1]
	v_pk_fma_f32 v[26:27], v[26:27], v[20:21], v[18:19] op_sel_hi:[1,0,1]
	s_waitcnt vmcnt(0)
	v_pk_fma_f32 v[12:13], v[24:25], v[84:85], v[30:31] op_sel_hi:[1,0,1]
	v_pk_fma_f32 v[10:11], v[22:23], v[84:85], v[2:3] op_sel_hi:[1,0,1]
	v_pk_fma_f32 v[20:21], v[24:25], v[72:73], v[4:5] op_sel_hi:[1,0,1]
	v_pk_fma_f32 v[18:19], v[22:23], v[72:73], v[6:7] op_sel_hi:[1,0,1]
	v_pk_fma_f32 v[16:17], v[24:25], v[38:39], v[8:9] op_sel_hi:[1,0,1]
	v_pk_fma_f32 v[14:15], v[22:23], v[38:39], v[34:35] op_sel_hi:[1,0,1]
	v_pk_fma_f32 v[8:9], v[24:25], v[40:41], v[36:37] op_sel_hi:[1,0,1]
	v_pk_fma_f32 v[6:7], v[22:23], v[40:41], v[60:61] op_sel_hi:[1,0,1]
	v_pk_fma_f32 v[4:5], v[24:25], v[68:69], v[28:29] op_sel_hi:[1,0,1]
	v_pk_fma_f32 v[2:3], v[22:23], v[68:69], v[26:27] op_sel_hi:[1,0,1]
	s_cbranch_scc1 .LBB0_42
	s_mul_i32 s9, s6, 5
	s_mul_i32 s6, s6, 0x5a000
	s_mul_hi_i32 s9, s9, 0x12000
	s_add_u32 s6, s16, s6
	s_addc_u32 s10, s17, s9
	s_ashr_i32 s9, s8, 31
	s_lshl_b64 s[8:9], s[8:9], 2
	s_add_u32 s8, s6, s8
	s_addc_u32 s9, s10, s9
	v_lshl_add_u64 v[22:23], s[8:9], 0, v[42:43]
	global_store_dwordx4 v42, v[10:13], s[8:9]
	s_nop 1
	v_add_co_u32_e32 v10, vcc, s30, v22
	s_nop 1
	v_addc_co_u32_e32 v11, vcc, 0, v23, vcc
	global_store_dwordx4 v[10:11], v[18:21], off
	v_add_co_u32_e32 v10, vcc, 0x24000, v22
	s_nop 1
	v_addc_co_u32_e32 v11, vcc, 0, v23, vcc
	global_store_dwordx4 v[10:11], v[14:17], off
	v_add_co_u32_e32 v10, vcc, 0x36000, v22
	s_nop 1
	v_addc_co_u32_e32 v11, vcc, 0, v23, vcc
	global_store_dwordx4 v[10:11], v[6:9], off
	s_nop 1
	v_add_co_u32_e32 v6, vcc, 0x48000, v22
	s_nop 1
	v_addc_co_u32_e32 v7, vcc, 0, v23, vcc
	global_store_dwordx4 v[6:7], v[2:5], off
	s_waitcnt lgkmcnt(0)
	s_branch .LBB0_10

.LBB0_98:
	v_mul_hi_i32 v3, v1, s16
	v_lshrrev_b32_e32 v4, 31, v3
	v_ashrrev_i32_e32 v3, 10, v3
	v_add_u32_e32 v3, v3, v4
	v_mul_i32_i24_e32 v4, 0x1200, v3
	v_mul_hi_i32_i24_e32 v73, 0x12000, v3
	v_mul_i32_i24_e32 v72, 0x12000, v3
	v_lshlrev_b32_e32 v3, 2, v4
	v_sub_u32_e32 v4, v2, v3
	v_ashrrev_i32_e32 v5, 31, v4
	v_lshlrev_b64 v[74:75], 2, v[4:5]
	v_lshl_add_u64 v[8:9], s[10:11], 0, v[74:75]
	v_lshl_add_u64 v[12:13], v[8:9], 0, v[72:73]
	v_add_co_u32_e32 v76, vcc, s17, v12
	v_lshl_add_u64 v[4:5], s[6:7], 0, v[74:75]
	s_nop 0
	v_addc_co_u32_e32 v77, vcc, 0, v13, vcc
	v_add_co_u32_e32 v78, vcc, s18, v12
	global_load_dwordx4 v[4:7], v[4:5], off nt
	s_nop 0
	v_addc_co_u32_e32 v79, vcc, 0, v13, vcc
	v_add_co_u32_e32 v80, vcc, s19, v12
	global_load_dwordx4 v[8:11], v[12:13], off nt
	s_nop 0
	v_addc_co_u32_e32 v81, vcc, 0, v13, vcc
	v_add_co_u32_e32 v82, vcc, s20, v12
	v_add_u32_e32 v1, s14, v1
	s_nop 0
	v_addc_co_u32_e32 v83, vcc, 0, v13, vcc
	v_add_co_u32_e32 v84, vcc, s21, v12
	v_lshl_add_u64 v[72:73], s[8:9], 0, v[72:73]
	s_nop 0
	v_addc_co_u32_e32 v85, vcc, 0, v13, vcc
	v_add_co_u32_e32 v86, vcc, s22, v12
	v_add_u32_e32 v2, s15, v2
	s_nop 0
	v_addc_co_u32_e32 v87, vcc, 0, v13, vcc
	v_add_co_u32_e32 v88, vcc, s23, v12
	v_lshl_add_u64 v[72:73], v[72:73], 0, v[74:75]
	s_nop 0
	v_addc_co_u32_e32 v89, vcc, 0, v13, vcc
	v_add_co_u32_e32 v90, vcc, s24, v12
	s_waitcnt vmcnt(0)
	v_pk_add_f32 v[6:7], v[6:7], v[10:11]
	v_addc_co_u32_e32 v91, vcc, 0, v13, vcc
	v_add_co_u32_e32 v92, vcc, s25, v12
	v_pk_add_f32 v[4:5], v[4:5], v[8:9]
	s_nop 0
	v_addc_co_u32_e32 v93, vcc, 0, v13, vcc
	v_add_co_u32_e32 v94, vcc, s26, v12
	s_nop 1
	v_addc_co_u32_e32 v95, vcc, 0, v13, vcc
	v_add_co_u32_e32 v96, vcc, s27, v12
	s_nop 1
	v_addc_co_u32_e32 v97, vcc, 0, v13, vcc
	v_add_co_u32_e32 v98, vcc, s29, v12
	s_nop 1
	v_addc_co_u32_e32 v99, vcc, 0, v13, vcc
	v_add_co_u32_e32 v100, vcc, s30, v12
	s_nop 1
	v_addc_co_u32_e32 v101, vcc, 0, v13, vcc
	v_add_co_u32_e32 v102, vcc, s31, v12
	s_nop 1
	v_addc_co_u32_e32 v103, vcc, 0, v13, vcc
	v_add_co_u32_e32 v104, vcc, s33, v12
	s_nop 1
	v_addc_co_u32_e32 v105, vcc, 0, v13, vcc
	global_load_dwordx4 v[12:15], v[76:77], off nt
	global_load_dwordx4 v[16:19], v[78:79], off nt
	global_load_dwordx4 v[20:23], v[80:81], off nt
	global_load_dwordx4 v[24:27], v[82:83], off nt
	global_load_dwordx4 v[28:31], v[84:85], off nt
	global_load_dwordx4 v[32:35], v[86:87], off nt
	global_load_dwordx4 v[36:39], v[88:89], off nt
	global_load_dwordx4 v[40:43], v[90:91], off nt
	global_load_dwordx4 v[44:47], v[92:93], off nt
	global_load_dwordx4 v[48:51], v[94:95], off nt
	global_load_dwordx4 v[52:55], v[96:97], off nt
	global_load_dwordx4 v[56:59], v[98:99], off nt
	global_load_dwordx4 v[60:63], v[100:101], off nt
	global_load_dwordx4 v[64:67], v[102:103], off nt
	global_load_dwordx4 v[68:71], v[104:105], off nt
	v_cmp_lt_i32_e32 vcc, s34, v1
	s_or_b64 s[12:13], vcc, s[12:13]
	s_waitcnt vmcnt(14)
	v_pk_add_f32 v[6:7], v[6:7], v[14:15]
	v_pk_add_f32 v[4:5], v[4:5], v[12:13]
	s_waitcnt vmcnt(13)
	v_pk_add_f32 v[6:7], v[6:7], v[18:19]
	v_pk_add_f32 v[4:5], v[4:5], v[16:17]
	s_waitcnt vmcnt(12)
	v_pk_add_f32 v[6:7], v[6:7], v[22:23]
	v_pk_add_f32 v[4:5], v[4:5], v[20:21]
	s_waitcnt vmcnt(11)
	v_pk_add_f32 v[6:7], v[6:7], v[26:27]
	v_pk_add_f32 v[4:5], v[4:5], v[24:25]
	s_waitcnt vmcnt(10)
	v_pk_add_f32 v[6:7], v[6:7], v[30:31]
	v_pk_add_f32 v[4:5], v[4:5], v[28:29]
	s_waitcnt vmcnt(9)
	v_pk_add_f32 v[6:7], v[6:7], v[34:35]
	v_pk_add_f32 v[4:5], v[4:5], v[32:33]
	s_waitcnt vmcnt(8)
	v_pk_add_f32 v[6:7], v[6:7], v[38:39]
	v_pk_add_f32 v[4:5], v[4:5], v[36:37]
	s_waitcnt vmcnt(7)
	v_pk_add_f32 v[6:7], v[6:7], v[42:43]
	v_pk_add_f32 v[4:5], v[4:5], v[40:41]
	s_waitcnt vmcnt(6)
	v_pk_add_f32 v[6:7], v[6:7], v[46:47]
	v_pk_add_f32 v[4:5], v[4:5], v[44:45]
	s_waitcnt vmcnt(5)
	v_pk_add_f32 v[6:7], v[6:7], v[50:51]
	v_pk_add_f32 v[4:5], v[4:5], v[48:49]
	s_waitcnt vmcnt(4)
	v_pk_add_f32 v[6:7], v[6:7], v[54:55]
	v_pk_add_f32 v[4:5], v[4:5], v[52:53]
	s_waitcnt vmcnt(3)
	v_pk_add_f32 v[6:7], v[6:7], v[58:59]
	v_pk_add_f32 v[4:5], v[4:5], v[56:57]
	s_waitcnt vmcnt(2)
	v_pk_add_f32 v[6:7], v[6:7], v[62:63]
	v_pk_add_f32 v[4:5], v[4:5], v[60:61]
	s_waitcnt vmcnt(1)
	v_pk_add_f32 v[6:7], v[6:7], v[66:67]
	v_pk_add_f32 v[4:5], v[4:5], v[64:65]
	s_waitcnt vmcnt(0)
	v_pk_add_f32 v[6:7], v[6:7], v[70:71]
	v_pk_add_f32 v[4:5], v[4:5], v[68:69]
	global_store_dwordx4 v[72:73], v[4:7], off
	s_andn2_b64 exec, exec, s[12:13]
	s_cbranch_execnz .LBB0_98

.LBB0_509:
	s_min_i32 s31, s34, 0x4000
	v_lshlrev_b32_e32 v147, 2, v128
	s_ashr_i32 s31, s31, 12
	global_load_dwordx4 v[34:37], v147, s[4:5] offset:16 nt
	global_load_dwordx4 v[30:33], v147, s[4:5] nt
	global_load_dwordx4 v[80:83], v147, s[4:5] offset:2064 nt
	global_load_dwordx4 v[38:41], v147, s[4:5] offset:2048 nt
	s_mul_i32 s4, s31, 0x4800
	s_ashr_i32 s5, s4, 31
	s_lshl_b64 s[4:5], s[4:5], 2
	s_add_u32 s4, s16, s4
	s_addc_u32 s5, s17, s5
	global_load_dwordx4 v[6:9], v147, s[28:29] offset:16 nt
	global_load_dwordx4 v[2:5], v147, s[28:29] nt
	global_load_dwordx4 v[58:61], v147, s[28:29] offset:2064 nt
	global_load_dwordx4 v[10:13], v147, s[28:29] offset:2048 nt
	s_add_u32 s28, s4, 0x1000
	s_addc_u32 s29, s5, 0
	global_load_dwordx4 v[50:53], v147, s[4:5] offset:16
	global_load_dwordx4 v[54:57], v147, s[4:5]
	global_load_dwordx4 v[72:75], v147, s[28:29] offset:16
	global_load_dwordx4 v[76:79], v147, s[28:29]
	global_load_dwordx4 v[42:45], v147, s[4:5] offset:2064
	global_load_dwordx4 v[46:49], v147, s[4:5] offset:2048
	global_load_dwordx4 v[62:65], v146, s[28:29] offset:16
	global_load_dwordx4 v[68:71], v146, s[28:29]
	s_cmpk_gt_i32 s34, 0x3fff
	s_cselect_b64 s[4:5], -1, 0
	s_and_b64 s[28:29], s[6:7], s[4:5]
	s_mov_b64 s[4:5], -1
	s_and_b64 vcc, exec, s[28:29]
	s_cbranch_vccnz .LBB0_511
	s_waitcnt vmcnt(0)
	v_mov_b64_e32 v[14:15], v[30:31]
	s_mov_b64 s[4:5], 0
	v_mov_b32_e32 v87, v83
	v_mov_b32_e32 v86, v82
	v_mov_b32_e32 v85, v81
	v_mov_b32_e32 v84, v80
	v_mov_b64_e32 v[16:17], v[32:33]
	v_mov_b64_e32 v[18:19], v[34:35]
	v_mov_b64_e32 v[20:21], v[36:37]
	v_mov_b64_e32 v[22:23], v[38:39]
	v_mov_b64_e32 v[24:25], v[40:41]
	v_mov_b64_e32 v[26:27], v[42:43]
	v_mov_b64_e32 v[28:29], v[44:45]
